# F phase: forward HGRN gate loads de-serialized (4 per row issued together instead of one per vmcnt(0) drain); forward HGRN items spread over all workgroups (waves 0-3); every workgroup one transpose i
# baseline (speedup 1.0000x reference)
;     __device__ __forceinline__ float* fp(size_t off) const { return (float*)(ws + off); }
; template <int DIR>
; __device__ __forceinline__ void hgrn_pass3_item(const Ctx& C, int l, int item) {
;     const int c = item & 31, hd = (item >> 5) & 3, b = item >> 7;
;     unsigned char* wl = C.lds + C.wave * 14336;
;     const float lb = hgrn_lb(C, l, hd * 64 + C.lane);
;     const int fr = C.lane & 15, quad = C.lane >> 4;
;     f32x4 Sacc[4][4]; float dectot = 1.f;
;     if (DIR == 1) {
;         hgrn_state_load(C.fp(OFF_S) + (size_t)((((1 * 8 + b) * 4 + hd) * 32) + (31 - c)) * 4096, Sacc, fr, quad);
;         hgrn_mfma<1>(C, l, 1, b, hd, 31 - c, Sacc, dectot, wl, lb);
;     } else {
;         hgrn_state_load(C.fp(OFF_S) + (size_t)((((0 * 8 + b) * 4 + hd) * 32) + c) * 4096, Sacc, fr, quad);
;         hgrn_mfma<2>(C, l, 0, b, hd, c, Sacc, dectot, wl, lb);
;     }
; }
; __global__ void __launch_bounds__(NTHR, 2) fwd_megakernel(Params prm) {
;     ...
;         for (int it = bid * 8 + C.wave; it < 1024; it += G * 8) hgrn_pass3_item<0>(C, l, it);
.LBB0_737:
	s_or_b64 exec, exec, s[0:1]
	s_waitcnt lgkmcnt(0)
	v_mov_b32_e32 v0, v224
	s_barrier
	s_mov_b64 s[0:1], 0
	v_mov_b32_e32 v0, v224
	s_mov_b64 s[30:31], 0
	v_readfirstlane_b32 s0, v0
	s_ashr_i32 s69, s0, 6
	s_add_u32 s38, s24, s30
	v_readlane_b32 s0, v253, 32
	s_addc_u32 s39, s25, s31
	s_add_i32 s68, s69, s0
	s_cmpk_lg_i32 s26, 0x100
	s_cbranch_scc1 .Lmy_h0_generic
	s_lshr_b32 s68, s0, 1
	s_add_i32 s68, s68, s69
	s_cmp_gt_u32 s69, 3
	s_cselect_b32 s68, 0x400, s68
.Lmy_h0_generic:
	s_cmpk_gt_i32 s68, 0x3ff
	v_and_b32_e32 v132, 63, v0
	s_cbranch_scc1 .LBB0_746
	v_lshrrev_b32_e32 v3, 4, v132
	v_and_b32_e32 v1, 15, v0
	v_lshlrev_b32_e32 v5, 8, v3
	v_or_b32_e32 v7, 16, v1
	v_or_b32_e32 v9, 32, v1
	v_or_b32_e32 v11, 48, v1
	v_or_b32_e32 v15, 0x440, v5
	v_or_b32_e32 v13, 0x400, v5
	v_or_b32_e32 v6, v15, v1
	v_or_b32_e32 v17, 0x480, v5
	v_or_b32_e32 v14, v15, v7
	v_or_b32_e32 v22, v15, v9
	v_or_b32_e32 v30, v15, v11
	v_or_b32_e32 v15, 0x840, v5
	s_mul_i32 s0, s69, 0x3800
	v_or_b32_e32 v4, v13, v1
	v_or_b32_e32 v8, v17, v1
	v_or_b32_e32 v12, v13, v7
	v_or_b32_e32 v16, v17, v7
	v_or_b32_e32 v20, v13, v9
	v_or_b32_e32 v24, v17, v9
	v_or_b32_e32 v28, v13, v11
	v_or_b32_e32 v32, v17, v11
	v_or_b32_e32 v13, 0x800, v5
	v_or_b32_e32 v38, v15, v1
	v_or_b32_e32 v17, 0x880, v5
	v_or_b32_e32 v46, v15, v7
	v_or_b32_e32 v54, v15, v9
	v_or_b32_e32 v62, v15, v11
	v_or_b32_e32 v15, 0xc40, v5
	v_lshlrev_b32_e32 v135, 2, v3
	v_lshlrev_b32_e32 v136, 3, v3
	v_bfe_u32 v0, v0, 2, 2
	s_add_i32 s70, s0, 0
	v_or_b32_e32 v19, 0x4c0, v5
	v_or_b32_e32 v36, v13, v1
	v_or_b32_e32 v40, v17, v1
	v_or_b32_e32 v44, v13, v7
	v_or_b32_e32 v48, v17, v7
	v_or_b32_e32 v52, v13, v9
	v_or_b32_e32 v56, v17, v9
	v_or_b32_e32 v60, v13, v11
	v_or_b32_e32 v66, v17, v11
	v_or_b32_e32 v13, 0xc00, v5
	v_or_b32_e32 v72, v15, v1
	v_or_b32_e32 v17, 0xc80, v5
	v_or_b32_e32 v80, v15, v7
	v_or_b32_e32 v88, v15, v9
	v_or_b32_e32 v96, v15, v11
	v_mul_u32_u24_e32 v3, 0x48, v1
	v_or_b32_e32 v15, v135, v0
	v_or_b32_e32 v0, v136, v0
	s_add_u32 s71, s38, 0x1a180000
	v_or_b32_e32 v10, v19, v1
	v_or_b32_e32 v18, v19, v7
	v_or_b32_e32 v26, v19, v9
	v_or_b32_e32 v34, v19, v11
	v_or_b32_e32 v19, 0x8c0, v5
	v_or_b32_e32 v70, v13, v1
	v_or_b32_e32 v74, v17, v1
	v_or_b32_e32 v78, v13, v7
	v_or_b32_e32 v82, v17, v7
	v_or_b32_e32 v86, v13, v9
	v_or_b32_e32 v90, v17, v9
	v_or_b32_e32 v94, v13, v11
	v_or_b32_e32 v98, v17, v11
	v_readlane_b32 s0, v254, 59
	v_lshlrev_b32_e32 v3, 1, v3
	v_and_b32_e32 v13, 48, v132
	v_lshlrev_b32_e32 v17, 3, v132
	v_mul_u32_u24_e32 v0, 0x48, v0
	s_addc_u32 s72, s39, 0
	v_or_b32_e32 v42, v19, v1
	v_or_b32_e32 v50, v19, v7
	v_or_b32_e32 v58, v19, v9
	v_or_b32_e32 v68, v19, v11
	v_or_b32_e32 v19, 0xcc0, v5
	v_readlane_b32 s1, v254, 60
	v_add3_u32 v138, s70, v3, v13
	v_sub_u32_e32 v13, v1, v135
	v_and_b32_e32 v17, 24, v17
	v_lshlrev_b32_e32 v0, 1, v0
	v_lshlrev_b32_e32 v64, 1, v1
	v_or_b32_e32 v2, v5, v1
	v_or_b32_e32 v76, v19, v1
	s_add_u32 s44, s38, 0x7000000
	v_lshl_or_b32 v133, s0, 8, v1
	v_add3_u32 v140, s70, v0, v17
	v_lshl_add_u64 v[0:1], s[38:39], 0, v[64:65]
	s_mov_b64 s[0:1], 0x4000000
	v_cmp_gt_i32_e64 s[4:5], 2, v13
	v_cmp_gt_i32_e64 s[42:43], 3, v13
	s_addc_u32 s45, s39, 0
	v_lshl_add_u64 v[102:103], v[0:1], 0, s[0:1]
	v_cmp_gt_i32_e64 s[0:1], 1, v13
	s_and_b64 s[46:47], s[42:43], s[4:5]
	v_or_b32_e32 v84, v19, v7
	v_or_b32_e32 v92, v19, v9
	v_or_b32_e32 v100, v19, v11
	v_add_u32_e32 v137, s70, v136
	v_mul_u32_u24_e32 v15, 0x90, v15
	v_cmp_gt_i32_e32 vcc, 0, v13
	v_or_b32_e32 v0, v5, v7
	v_or_b32_e32 v106, v5, v9
	v_or_b32_e32 v108, v5, v11
	s_and_b64 s[48:49], s[46:47], s[0:1]
	v_lshl_add_u32 v134, v132, 2, s70
	v_add3_u32 v139, s70, v15, v17
	v_add_u32_e32 v141, v137, v3
	v_lshl_add_u64 v[104:105], s[44:45], 0, v[64:65]
	v_lshlrev_b32_e32 v142, 2, v2
	v_lshlrev_b32_e32 v143, 2, v0
	v_lshlrev_b32_e32 v144, 2, v106
	v_lshlrev_b32_e32 v145, 2, v108
	v_lshlrev_b32_e32 v146, 2, v4
	v_lshlrev_b32_e32 v147, 2, v6
	v_lshlrev_b32_e32 v148, 2, v8
	v_lshlrev_b32_e32 v149, 2, v10
	v_lshlrev_b32_e32 v150, 2, v12
	v_lshlrev_b32_e32 v151, 2, v14
	v_lshlrev_b32_e32 v152, 2, v16
	v_lshlrev_b32_e32 v153, 2, v18
	v_lshlrev_b32_e32 v154, 2, v20
	v_lshlrev_b32_e32 v155, 2, v22
	v_lshlrev_b32_e32 v156, 2, v24
	v_lshlrev_b32_e32 v157, 2, v26
	v_lshlrev_b32_e32 v158, 2, v28
	v_lshlrev_b32_e32 v159, 2, v30
	v_lshlrev_b32_e32 v160, 2, v32
	v_lshlrev_b32_e32 v161, 2, v34
	v_lshlrev_b32_e32 v162, 2, v36
	v_lshlrev_b32_e32 v163, 2, v38
	v_lshlrev_b32_e32 v164, 2, v40
	v_lshlrev_b32_e32 v165, 2, v42
	v_lshlrev_b32_e32 v166, 2, v44
	v_lshlrev_b32_e32 v167, 2, v46
	v_lshlrev_b32_e32 v168, 2, v48
	v_lshlrev_b32_e32 v169, 2, v50
	v_lshlrev_b32_e32 v170, 2, v52
	v_lshlrev_b32_e32 v171, 2, v54
	v_lshlrev_b32_e32 v172, 2, v56
	v_lshlrev_b32_e32 v173, 2, v58
	v_lshlrev_b32_e32 v174, 2, v60
	v_lshlrev_b32_e32 v175, 2, v62
	v_lshlrev_b32_e32 v176, 2, v66
	v_lshlrev_b32_e32 v177, 2, v68
	v_lshlrev_b32_e32 v183, 2, v70
	v_lshlrev_b32_e32 v192, 2, v72
	v_lshlrev_b32_e32 v193, 2, v74
	v_lshlrev_b32_e32 v194, 2, v76
	v_lshlrev_b32_e32 v195, 2, v78
	v_lshlrev_b32_e32 v196, 2, v80
	v_lshlrev_b32_e32 v197, 2, v82
	v_lshlrev_b32_e32 v198, 2, v84
	v_lshlrev_b32_e32 v199, 2, v86
	v_lshlrev_b32_e32 v200, 2, v88
	v_lshlrev_b32_e32 v201, 2, v90
	v_lshlrev_b32_e32 v202, 2, v92
	v_lshlrev_b32_e32 v203, 2, v94
	v_lshlrev_b32_e32 v204, 2, v96
	v_lshlrev_b32_e32 v205, 2, v98
	v_lshlrev_b32_e32 v206, 2, v100
	s_and_b64 s[50:51], s[48:49], vcc
	s_mov_b32 s73, s68

; __device__ __forceinline__ bf16_t f2bf(float f) { return (bf16_t)(cvt_pk_bf16(f, 0.f) & 0xffffu); }
; __device__ __forceinline__ float bf2f(bf16_t b) { return __uint_as_float(((unsigned)b) << 16); }
; __device__ __forceinline__ float sigmoidf_(float x) { return 1.0f / (1.0f + __expf(-x)); }
; template <int MODE>
; __device__ __forceinline__ void hgrn_mfma(const Ctx& C, int l, int z, int b, int hd, int c, f32x4 (&Sacc)[4][4], float& dectot, unsigned char* wl, float lb) {
;     ...
;             bf16_t fv[16], qv[16], vv[16];
;             const int st0 = c * 128 + sc * 32 + g8 * 16; const int tq0 = z ? 4095 - st0 : st0;
;             const bf16_t* row0 = pa + (size_t)(b * SEQ + tq0) * 1280; const ptrdiff_t rstep = z ? -1280 : 1280;
; #pragma unroll
;             for (int t = 0; t < 16; ++t) { const bf16_t* row = row0 + rstep * t; fv[t] = row[fcol]; vv[t] = row[vcol]; if (MODE != 0) qv[t] = row[qcol]; }
; #pragma unroll
;             for (int t = 0; t < 16; ++t) {
;                 const float fl = bf2f(fv[t]);
;                 const float sg = sigmoidf_(fl);
;                 const float f = lb + (1.0f - lb) * sg, kk = (1.0f - lb) * (1.0f - sg);
;                 bacc += __logf(fmaxf(f, 1e-30f));
;                 Kb[(g8 * 16 + t) * HPT + lane] = f2bf(kk * __expf(fminf(-bacc, 80.f)));
;                 if (MODE != 0) Qt[(g8 * 16 + t) * HPT + lane] = f2bf(bf2f(qv[t]) * __expf(fmaxf(bacc, -80.f)));
;                 Vv[(g8 * 16 + t) * HPT + lane] = vv[t];
.LBB0_743:
	s_lshl_b32 s0, s67, 4
	v_cndmask_b32_e64 v61, 0, 1, s[52:53]
	s_mul_i32 s1, s67, 0x480
	s_or_b32 s0, s0, s76
	v_cmp_ne_u32_e64 s[4:5], 1, v61
	v_or_b32_e32 v61, s1, v132
	s_mul_hi_i32 s1, s0, 0xa00
	s_mulk_i32 s0, 0xa00
	s_add_u32 s0, s44, s0
	v_lshlrev_b32_e32 v62, 1, v207
	s_addc_u32 s1, s45, s1
	global_load_ushort v63, v62, s[0:1] offset:512
	global_load_ushort v64, v62, s[0:1] offset:1536
	global_load_ushort v70, v62, s[0:1] offset:3072
	global_load_ushort v71, v215, s[0:1] offset:2560
	s_add_u32 s6, s0, 0x1400
	s_addc_u32 s7, s1, 0
	global_load_ushort v72, v228, s[6:7]
	global_load_ushort v73, v62, s[6:7]
	global_load_ushort v74, v215, s[6:7]
	s_add_u32 s6, s0, 0x1e00
	s_addc_u32 s7, s1, 0
	global_load_ushort v75, v228, s[6:7]
	global_load_ushort v76, v62, s[6:7]
	global_load_ushort v77, v215, s[6:7]
	s_add_u32 s6, s0, 0x2800
	s_addc_u32 s7, s1, 0
	global_load_ushort v78, v62, s[6:7]
	global_load_ushort v81, v62, s[0:1] offset:2560
	global_load_ushort v82, v62, s[0:1]
	global_load_ushort v83, v228, s[6:7]
	global_load_ushort v84, v215, s[6:7]
	s_add_u32 s6, s0, 0x3200
	s_addc_u32 s7, s1, 0
	s_add_u32 s8, s0, 0x3c00
	global_load_ushort v85, v215, s[6:7]
	global_load_ushort v86, v228, s[6:7]
	global_load_ushort v87, v62, s[6:7]
	s_addc_u32 s9, s1, 0
	s_add_u32 s6, s0, 0x4600
	global_load_ushort v88, v215, s[8:9]
	global_load_ushort v89, v228, s[8:9]
	global_load_ushort v90, v62, s[8:9]
	s_addc_u32 s7, s1, 0
	s_add_u32 s8, s0, 0x5000
	global_load_ushort v91, v215, s[6:7]
	global_load_ushort v92, v228, s[6:7]
	global_load_ushort v93, v62, s[6:7]
	s_addc_u32 s9, s1, 0
	s_add_u32 s6, s0, 0x5a00
	global_load_ushort v94, v215, s[8:9]
	global_load_ushort v95, v228, s[8:9]
	global_load_ushort v96, v62, s[8:9]
	s_addc_u32 s7, s1, 0
	s_add_u32 s8, s0, 0x6400
	global_load_ushort v97, v215, s[6:7]
	global_load_ushort v98, v228, s[6:7]
	global_load_ushort v99, v62, s[6:7]
	s_addc_u32 s9, s1, 0
	s_add_u32 s6, s0, 0x6e00
	global_load_ushort v100, v215, s[8:9]
	global_load_ushort v101, v228, s[8:9]
	global_load_ushort v110, v62, s[8:9]
	s_addc_u32 s7, s1, 0
	s_add_u32 s8, s0, 0x7800
	global_load_ushort v111, v215, s[6:7]
	global_load_ushort v112, v228, s[6:7]
	global_load_ushort v113, v62, s[6:7]
	s_addc_u32 s9, s1, 0
	global_load_ushort v114, v215, s[8:9]
	global_load_ushort v115, v228, s[8:9]
	global_load_ushort v116, v62, s[8:9]
	s_add_u32 s6, s0, 0x8200
	s_addc_u32 s7, s1, 0
	s_add_u32 s8, s0, 0x8c00
	global_load_ushort v117, v215, s[6:7]
	global_load_ushort v118, v228, s[6:7]
	global_load_ushort v119, v62, s[6:7]
	s_addc_u32 s9, s1, 0
	s_add_u32 s0, s0, 0x9600
	global_load_ushort v120, v215, s[8:9]
	global_load_ushort v121, v228, s[8:9]
	global_load_ushort v122, v62, s[8:9]
	s_addc_u32 s1, s1, 0
	global_load_ushort v123, v215, s[0:1]
	global_load_ushort v124, v228, s[0:1]
	global_load_ushort v125, v62, s[0:1]
	v_lshl_add_u32 v61, v61, 1, s70
	s_mov_b64 s[52:53], 0
	s_mov_b32 s67, 1
	s_waitcnt vmcnt(47)
	v_lshlrev_b32_e32 v62, 16, v63
	v_mul_f32_e32 v62, 0xbfb8aa3b, v62
	s_waitcnt vmcnt(45)
	v_lshlrev_b32_e32 v63, 16, v70
	v_mul_f32_e32 v63, 0xbfb8aa3b, v63
	ds_write_b16 v61, v64 offset:9216
	v_exp_f32_e32 v62, v62
	v_exp_f32_e32 v63, v63
	s_waitcnt vmcnt(43)
	v_lshlrev_b32_e32 v64, 16, v72
	v_mul_f32_e32 v64, 0xbfb8aa3b, v64
	v_exp_f32_e32 v64, v64
	s_waitcnt vmcnt(40)
	v_lshlrev_b32_e32 v70, 16, v75
	v_mul_f32_e32 v70, 0xbfb8aa3b, v70
	v_lshlrev_b32_e32 v80, 16, v73
	v_add_f32_e32 v73, 1.0, v62
	v_add_f32_e32 v63, 1.0, v63
	v_exp_f32_e32 v62, v70
	s_waitcnt vmcnt(34)
	v_lshlrev_b32_e32 v70, 16, v83
	v_mul_f32_e32 v70, 0xbfb8aa3b, v70
	v_add_f32_e32 v128, 1.0, v64
	v_exp_f32_e32 v64, v70
	s_waitcnt vmcnt(31)
	v_lshlrev_b32_e32 v70, 16, v86
	ds_write_b16 v61, v85 offset:9936
	ds_write_b16 v61, v77 offset:9648
	s_waitcnt vmcnt(30)
	v_lshlrev_b32_e32 v77, 16, v87
	v_mul_f32_e32 v70, 0xbfb8aa3b, v70
	v_add_f32_e32 v129, 1.0, v62
	v_exp_f32_e32 v62, v70
	s_waitcnt vmcnt(28)
	v_lshlrev_b32_e32 v70, 16, v89
	ds_write_b16 v61, v88 offset:10080
	ds_write_b16 v61, v71 offset:9360
	ds_write_b16 v61, v74 offset:9504
	s_waitcnt vmcnt(27)
	v_lshlrev_b32_e32 v74, 16, v90
	v_mul_f32_e32 v70, 0xbfb8aa3b, v70
	v_lshlrev_b32_e32 v79, 16, v76
	ds_write_b16 v61, v84 offset:9792
	v_add_f32_e32 v131, 1.0, v64
	v_exp_f32_e32 v64, v70
	s_waitcnt vmcnt(25)
	v_lshlrev_b32_e32 v70, 16, v92
	s_waitcnt vmcnt(24)
	v_lshlrev_b32_e32 v72, 16, v93
	v_mul_f32_e32 v70, 0xbfb8aa3b, v70
	v_add_f32_e32 v180, 1.0, v62
	v_exp_f32_e32 v62, v70
	s_waitcnt vmcnt(22)
	v_lshlrev_b32_e32 v70, 16, v95
	ds_write_b16 v61, v94 offset:10368
	s_waitcnt vmcnt(21)
	v_lshlrev_b32_e32 v71, 16, v96
	v_mul_f32_e32 v70, 0xbfb8aa3b, v70
	v_add_f32_e32 v188, 1.0, v64
	v_exp_f32_e32 v70, v70
	s_waitcnt vmcnt(19)
	v_lshlrev_b32_e32 v98, 16, v98
	ds_write_b16 v61, v97 offset:10512
	v_mul_f32_e32 v97, 0xbfb8aa3b, v98
	s_waitcnt vmcnt(18)
	v_lshlrev_b32_e32 v64, 16, v99
	v_add_f32_e32 v99, 1.0, v62
	v_exp_f32_e32 v97, v97
	s_waitcnt vmcnt(16)
	v_lshlrev_b32_e32 v101, 16, v101
	v_rcp_f32_e32 v73, v73
	ds_write_b16 v61, v91 offset:10224
	ds_write_b16 v61, v100 offset:10656
	v_mul_f32_e32 v93, 0xbfb8aa3b, v101
	v_fma_f32 v100, v213, v73, v208
	v_sub_f32_e32 v73, 1.0, v73
	v_rcp_f32_e32 v75, v63
	s_waitcnt vmcnt(15)
	v_lshlrev_b32_e32 v62, 16, v110
	v_add_f32_e32 v101, 1.0, v70
	v_exp_f32_e32 v93, v93
	s_waitcnt vmcnt(13)
	v_lshlrev_b32_e32 v70, 16, v112
	v_mul_f32_e32 v110, v213, v73
	v_max_f32_e32 v73, 0xda24260, v100
	v_fma_f32 v100, v213, v75, v208
	v_sub_f32_e32 v75, 1.0, v75
	v_rcp_f32_e32 v76, v128
	v_mul_f32_e32 v70, 0xbfb8aa3b, v70
	v_mul_f32_e32 v112, v213, v75
	v_max_f32_e32 v75, 0xda24260, v100
	v_cmp_gt_f32_e32 vcc, s54, v73
	s_waitcnt vmcnt(12)
; __device__ __forceinline__ bf16_t f2bf(float f) { return (bf16_t)(cvt_pk_bf16(f, 0.f) & 0xffffu); }
; __device__ __forceinline__ float bf2f(bf16_t b) { return __uint_as_float(((unsigned)b) << 16); }
; __device__ __forceinline__ float sigmoidf_(float x) { return 1.0f / (1.0f + __expf(-x)); }
; template <int MODE>
; __device__ __forceinline__ void hgrn_mfma(const Ctx& C, int l, int z, int b, int hd, int c, f32x4 (&Sacc)[4][4], float& dectot, unsigned char* wl, float lb) {
;     ...
;             for (int t = 0; t < 16; ++t) {
;                 const float fl = bf2f(fv[t]);
;                 const float sg = sigmoidf_(fl);
;                 const float f = lb + (1.0f - lb) * sg, kk = (1.0f - lb) * (1.0f - sg);
;                 bacc += __logf(fmaxf(f, 1e-30f));
;                 Kb[(g8 * 16 + t) * HPT + lane] = f2bf(kk * __expf(fminf(-bacc, 80.f)));
;                 if (MODE != 0) Qt[(g8 * 16 + t) * HPT + lane] = f2bf(bf2f(qv[t]) * __expf(fmaxf(bacc, -80.f)));
;                 Vv[(g8 * 16 + t) * HPT + lane] = vv[t];
	v_lshlrev_b32_e32 v63, 16, v113
	v_fma_f32 v100, v213, v76, v208
	v_sub_f32_e32 v76, 1.0, v76
	v_add_f32_e32 v97, 1.0, v97
	v_exp_f32_e32 v126, v70
	s_waitcnt vmcnt(9)
	v_lshlrev_b32_e32 v70, 16, v116
	ds_write_b16 v61, v114 offset:10944
	v_cndmask_b32_e64 v114, 0, 32, vcc
	v_cndmask_b32_e32 v116, 0, v225, vcc
	v_cmp_gt_f32_e32 vcc, s54, v75
	v_lshlrev_b32_e32 v115, 16, v115
	v_mul_f32_e32 v127, v213, v76
	v_max_f32_e32 v76, 0xda24260, v100
	v_rcp_f32_e32 v83, v129
	v_cndmask_b32_e64 v128, 0, 32, vcc
	v_cndmask_b32_e32 v129, 0, v225, vcc
	v_mul_f32_e32 v115, 0xbfb8aa3b, v115
	v_ldexp_f32 v114, v73, v114
	v_fma_f32 v130, v213, v83, v208
	v_add_f32_e32 v93, 1.0, v93
	v_cmp_gt_f32_e32 vcc, s54, v76
	v_exp_f32_e32 v115, v115
	s_waitcnt vmcnt(7)
	v_lshlrev_b32_e32 v118, 16, v118
	s_waitcnt vmcnt(6)
	v_lshlrev_b32_e32 v73, 16, v119
	ds_write_b16 v61, v117 offset:11088
	v_log_f32_e32 v114, v114
	v_ldexp_f32 v75, v75, v128
	v_cndmask_b32_e64 v117, 0, 32, vcc
	v_cndmask_b32_e32 v119, 0, v225, vcc
	v_max_f32_e32 v128, 0xda24260, v130
	v_rcp_f32_e32 v85, v131
	v_mul_f32_e32 v118, 0xbfb8aa3b, v118
	v_log_f32_e32 v178, v75
	v_ldexp_f32 v76, v76, v117
	v_fma_f32 v117, v213, v85, v208
	v_cmp_gt_f32_e32 vcc, s54, v128
	ds_write_b16 v61, v111 offset:10800
	v_add_f32_e32 v126, 1.0, v126
	v_exp_f32_e32 v118, v118
	s_waitcnt vmcnt(4)
	v_lshlrev_b32_e32 v121, 16, v121
	s_waitcnt vmcnt(3)
	v_lshlrev_b32_e32 v75, 16, v122
	ds_write_b16 v61, v120 offset:11232
	v_log_f32_e32 v120, v76
	v_cndmask_b32_e64 v76, 0, 32, vcc
	v_cndmask_b32_e32 v122, 0, v225, vcc
	v_max_f32_e32 v117, 0xda24260, v117
	v_rcp_f32_e32 v88, v180
	v_mul_f32_e32 v121, 0xbfb8aa3b, v121
	v_ldexp_f32 v128, v128, v76
	v_fma_f32 v189, v213, v88, v208
	v_cmp_gt_f32_e32 vcc, s54, v117
	v_add_f32_e32 v115, 1.0, v115
	v_exp_f32_e32 v121, v121
	s_waitcnt vmcnt(1)
	v_lshlrev_b32_e32 v124, 16, v124
	s_waitcnt vmcnt(0)
	v_lshlrev_b32_e32 v76, 16, v125
	ds_write_b16 v61, v123 offset:11376
	v_mul_f32_e32 v123, 0x3f317217, v114
	v_log_f32_e32 v125, v128
	v_cndmask_b32_e64 v128, 0, 32, vcc
	v_cndmask_b32_e32 v190, 0, v225, vcc
	v_max_f32_e32 v189, 0xda24260, v189
	v_rcp_f32_e32 v84, v188
	v_mul_f32_e32 v124, 0xbfb8aa3b, v124
	v_fma_f32 v123, v114, s56, -v123
	v_mul_f32_e32 v191, 0x3f317217, v178
	v_ldexp_f32 v117, v117, v128
	v_fma_f32 v128, v213, v84, v208
	v_cmp_gt_f32_e32 vcc, s54, v189
	v_add_f32_e32 v118, 1.0, v118
	v_exp_f32_e32 v124, v124
	v_fmac_f32_e32 v123, 0x3377d1cf, v114
	v_fma_f32 v191, v178, s56, -v191
	v_mul_f32_e32 v223, 0x3f317217, v120
	v_log_f32_e32 v117, v117
	v_cndmask_b32_e64 v229, 0, 32, vcc
	v_cndmask_b32_e32 v230, 0, v225, vcc
	v_max_f32_e32 v128, 0xda24260, v128
	v_rcp_f32_e32 v86, v99
	v_fmac_f32_e32 v123, 0x3f317217, v114
	v_cmp_lt_f32_e64 s[0:1], |v114|, s57
	v_fmac_f32_e32 v191, 0x3377d1cf, v178
	v_fma_f32 v223, v120, s56, -v223
	v_ldexp_f32 v189, v189, v229
	v_fma_f32 v229, v213, v86, v208
	v_cmp_gt_f32_e32 vcc, s54, v128
	v_fmac_f32_e32 v191, 0x3f317217, v178
	v_cmp_lt_f32_e64 s[18:19], |v178|, s57
	v_add_f32_e32 v121, 1.0, v121
	v_cndmask_b32_e64 v114, v114, v123, s[0:1]
	v_fmac_f32_e32 v223, 0x3377d1cf, v120
	v_mul_f32_e32 v123, 0x3f317217, v125
	v_log_f32_e32 v189, v189
	v_cndmask_b32_e64 v231, 0, 32, vcc
	v_cndmask_b32_e32 v232, 0, v225, vcc
	v_max_f32_e32 v229, 0xda24260, v229
	v_rcp_f32_e32 v87, v101
	v_fmac_f32_e32 v223, 0x3f317217, v120
	v_cmp_lt_f32_e64 s[0:1], |v120|, s57
	v_sub_f32_e32 v114, v114, v116
	v_cndmask_b32_e64 v116, v178, v191, s[18:19]
	v_fma_f32 v123, v125, s56, -v123
	v_ldexp_f32 v128, v128, v231
	v_fma_f32 v178, v213, v87, v208
	v_cmp_gt_f32_e32 vcc, s54, v229
	v_add_f32_e32 v124, 1.0, v124
	v_add_f32_e32 v60, v60, v114
	v_sub_f32_e32 v114, v116, v129
	v_cndmask_b32_e64 v116, v120, v223, s[0:1]
	v_fmac_f32_e32 v123, 0x3377d1cf, v125
	v_mul_f32_e32 v120, 0x3f317217, v117
	v_log_f32_e32 v128, v128
	v_cndmask_b32_e64 v129, 0, 32, vcc
	v_cndmask_b32_e32 v191, 0, v225, vcc
	v_max_f32_e32 v178, 0xda24260, v178
	v_fmac_f32_e32 v123, 0x3f317217, v125
	v_cmp_lt_f32_e64 s[0:1], |v125|, s57
	v_rcp_f32_e32 v89, v97
	v_min_f32_e64 v223, -v60, s60
	v_max_f32_e32 v231, 0xc2a00000, v60
	v_add_f32_e32 v60, v60, v114
	v_sub_f32_e32 v114, v116, v119
	v_fma_f32 v116, v117, s56, -v120
	v_ldexp_f32 v119, v229, v129
	v_cmp_gt_f32_e32 vcc, s54, v178
	v_fma_f32 v120, v213, v89, v208
	v_mul_f32_e32 v181, 0x3fb8aa3b, v223
	v_mul_f32_e32 v223, 0x3fb8aa3b, v231
	v_min_f32_e64 v229, -v60, s60
	v_max_f32_e32 v231, 0xc2a00000, v60
	v_add_f32_e32 v60, v60, v114
	v_cndmask_b32_e64 v114, v125, v123, s[0:1]
	v_fmac_f32_e32 v116, 0x3377d1cf, v117
	v_mul_f32_e32 v123, 0x3f317217, v189
	v_log_f32_e32 v119, v119
	v_cndmask_b32_e64 v125, 0, 32, vcc
	v_fmac_f32_e32 v116, 0x3f317217, v117
	v_cmp_lt_f32_e64 s[0:1], |v117|, s57
	v_cndmask_b32_e32 v233, 0, v225, vcc
	v_max_f32_e32 v120, 0xda24260, v120
	v_rcp_f32_e32 v90, v93
	v_exp_f32_e32 v97, v181
	v_exp_f32_e32 v180, v223
	v_mul_f32_e32 v181, 0x3fb8aa3b, v229
	v_mul_f32_e32 v223, 0x3fb8aa3b, v231
	v_min_f32_e64 v229, -v60, s60
	v_max_f32_e32 v231, 0xc2a00000, v60
	v_sub_f32_e32 v114, v114, v122
	v_fma_f32 v122, v189, s56, -v123
	v_ldexp_f32 v123, v178, v125
	v_fma_f32 v125, v213, v90, v208
	v_exp_f32_e32 v130, v181
	v_exp_f32_e32 v178, v223
	v_mul_f32_e32 v181, 0x3fb8aa3b, v229
	v_mul_f32_e32 v223, 0x3fb8aa3b, v231
	v_add_f32_e32 v60, v60, v114
	v_cndmask_b32_e64 v114, v117, v116, s[0:1]
	v_fmac_f32_e32 v122, 0x3377d1cf, v189
	v_mul_f32_e32 v116, 0x3f317217, v128
	v_log_f32_e32 v117, v123
	v_cmp_gt_f32_e32 vcc, s54, v120
	s_nop 0
	s_nop 0
	v_cndmask_b32_e64 v123, 0, 32, vcc
	v_fmac_f32_e32 v122, 0x3f317217, v189
	v_cmp_lt_f32_e64 s[0:1], |v189|, s57
; __device__ __forceinline__ bf16_t f2bf(float f) { return (bf16_t)(cvt_pk_bf16(f, 0.f) & 0xffffu); }
; __device__ __forceinline__ float bf2f(bf16_t b) { return __uint_as_float(((unsigned)b) << 16); }
; __device__ __forceinline__ float sigmoidf_(float x) { return 1.0f / (1.0f + __expf(-x)); }
; template <int MODE>
; __device__ __forceinline__ void hgrn_mfma(const Ctx& C, int l, int z, int b, int hd, int c, f32x4 (&Sacc)[4][4], float& dectot, unsigned char* wl, float lb) {
;     ...
;             for (int t = 0; t < 16; ++t) {
;                 const float fl = bf2f(fv[t]);
;                 const float sg = sigmoidf_(fl);
;                 const float f = lb + (1.0f - lb) * sg, kk = (1.0f - lb) * (1.0f - sg);
;                 bacc += __logf(fmaxf(f, 1e-30f));
;                 Kb[(g8 * 16 + t) * HPT + lane] = f2bf(kk * __expf(fminf(-bacc, 80.f)));
;                 if (MODE != 0) Qt[(g8 * 16 + t) * HPT + lane] = f2bf(bf2f(qv[t]) * __expf(fmaxf(bacc, -80.f)));
;                 Vv[(g8 * 16 + t) * HPT + lane] = vv[t];
;             }
	v_cndmask_b32_e32 v229, 0, v225, vcc
	v_max_f32_e32 v125, 0xda24260, v125
	v_rcp_f32_e32 v92, v126
	v_exp_f32_e32 v98, v181
	v_exp_f32_e32 v181, v223
	v_min_f32_e64 v188, -v60, s60
	v_max_f32_e32 v223, 0xc2a00000, v60
	v_sub_f32_e32 v114, v114, v190
	v_fma_f32 v116, v128, s56, -v116
	v_lshlrev_b32_e32 v82, 16, v82
	v_ldexp_f32 v120, v120, v123
	v_fma_f32 v123, v213, v92, v208
	v_mul_f32_e32 v126, 0x3fb8aa3b, v188
	v_mul_f32_e32 v188, 0x3fb8aa3b, v223
	v_add_f32_e32 v60, v60, v114
	v_cndmask_b32_e64 v114, v189, v122, s[0:1]
	v_fmac_f32_e32 v116, 0x3377d1cf, v128
	v_mul_f32_e32 v122, 0x3f317217, v119
	v_cmp_gt_f32_e32 vcc, s54, v125
	v_lshlrev_b32_e32 v81, 16, v81
	v_log_f32_e32 v120, v120
	v_cndmask_b32_e64 v189, 0, 32, vcc
	v_fmac_f32_e32 v116, 0x3f317217, v128
	v_cmp_lt_f32_e64 s[0:1], |v128|, s57
	v_cndmask_b32_e32 v190, 0, v225, vcc
	v_max_f32_e32 v123, 0xda24260, v123
	v_rcp_f32_e32 v91, v115
	v_mul_f32_e32 v96, v110, v97
	v_mul_f32_e32 v82, v180, v82
	v_exp_f32_e32 v97, v126
	v_exp_f32_e32 v110, v188
	v_min_f32_e64 v115, -v60, s60
	v_max_f32_e32 v126, 0xc2a00000, v60
	v_sub_f32_e32 v114, v114, v230
	v_fma_f32 v122, v119, s56, -v122
	v_ldexp_f32 v125, v125, v189
	v_fma_f32 v180, v213, v91, v208
	v_cvt_pk_bf16_f32 v96, v96, s0
	v_cvt_pk_bf16_f32 v82, v82, s0
	v_mul_f32_e32 v111, v112, v130
	v_mul_f32_e32 v81, v178, v81
	v_mul_f32_e32 v112, 0x3fb8aa3b, v115
	v_mul_f32_e32 v113, 0x3fb8aa3b, v126
	v_add_f32_e32 v60, v60, v114
	v_cndmask_b32_e64 v114, v128, v116, s[0:1]
	v_fmac_f32_e32 v122, 0x3377d1cf, v119
	v_mul_f32_e32 v115, 0x3f317217, v117
	v_cmp_gt_f32_e32 vcc, s54, v123
	v_cmp_lt_f32_e64 s[0:1], |v119|, s57
	v_sub_f32_e32 v83, 1.0, v83
	v_log_f32_e32 v116, v125
	v_cndmask_b32_e64 v125, 0, 32, vcc
	v_fmac_f32_e32 v122, 0x3f317217, v119
	v_cndmask_b32_e32 v126, 0, v225, vcc
	v_max_f32_e32 v128, 0xda24260, v180
	v_rcp_f32_e32 v93, v118
	ds_write_b16 v61, v96 offset:4608
	ds_write_b16 v61, v82
	v_cvt_pk_bf16_f32 v82, v111, s0
	v_cvt_pk_bf16_f32 v81, v81, s0
	v_mul_f32_e32 v96, v127, v98
	v_mul_f32_e32 v80, v181, v80
	v_exp_f32_e32 v98, v112
	v_exp_f32_e32 v111, v113
	v_min_f32_e64 v112, -v60, s60
	v_max_f32_e32 v113, 0xc2a00000, v60
	v_fma_f32 v115, v117, s56, -v115
	v_mul_f32_e32 v83, v213, v83
	v_sub_f32_e32 v114, v114, v232
	v_ldexp_f32 v118, v123, v125
	v_fma_f32 v123, v213, v93, v208
	ds_write_b16 v61, v82 offset:4752
	ds_write_b16 v61, v81 offset:144
	v_cvt_pk_bf16_f32 v81, v96, s0
	v_cvt_pk_bf16_f32 v80, v80, s0
	v_mul_f32_e32 v82, 0x3fb8aa3b, v112
	v_mul_f32_e32 v96, 0x3fb8aa3b, v113
	v_cndmask_b32_e64 v99, v119, v122, s[0:1]
	v_fmac_f32_e32 v115, 0x3377d1cf, v117
	v_cmp_gt_f32_e32 vcc, s54, v128
	v_sub_f32_e32 v85, 1.0, v85
	v_add_f32_e32 v60, v60, v114
	v_mul_f32_e32 v101, 0x3f317217, v120
	v_log_f32_e32 v112, v118
	v_cndmask_b32_e64 v113, 0, 32, vcc
	v_fmac_f32_e32 v115, 0x3f317217, v117
	v_cmp_lt_f32_e64 s[0:1], |v117|, s57
	v_cndmask_b32_e32 v114, 0, v225, vcc
	v_max_f32_e32 v118, 0xda24260, v123
	v_rcp_f32_e32 v95, v121
	ds_write_b16 v61, v81 offset:4896
	ds_write_b16 v61, v80 offset:288
	v_mul_f32_e32 v80, v83, v97
	v_mul_f32_e32 v79, v110, v79
	v_exp_f32_e32 v81, v82
	v_exp_f32_e32 v82, v96
	v_sub_f32_e32 v97, v99, v191
	v_lshlrev_b32_e32 v78, 16, v78
	v_mul_f32_e32 v85, v213, v85
	v_min_f32_e64 v83, -v60, s60
	v_max_f32_e32 v96, 0xc2a00000, v60
	v_fma_f32 v99, v120, s56, -v101
	v_ldexp_f32 v101, v128, v113
	v_fma_f32 v110, v213, v95, v208
	v_cvt_pk_bf16_f32 v80, v80, s0
	v_cvt_pk_bf16_f32 v79, v79, s0
	v_add_f32_e32 v60, v60, v97
	v_cndmask_b32_e64 v97, v117, v115, s[0:1]
	v_cmp_gt_f32_e64 s[0:1], s54, v118
	v_sub_f32_e32 v88, 1.0, v88
	v_mul_f32_e32 v83, 0x3fb8aa3b, v83
	v_mul_f32_e32 v96, 0x3fb8aa3b, v96
	v_fmac_f32_e32 v99, 0x3377d1cf, v120
	v_mul_f32_e32 v100, 0x3f317217, v116
	v_log_f32_e32 v101, v101
	v_cndmask_b32_e64 v113, 0, 32, s[0:1]
	v_max_f32_e32 v110, 0xda24260, v110
	v_rcp_f32_e32 v94, v124
	ds_write_b16 v61, v80 offset:5040
	ds_write_b16 v61, v79 offset:432
	v_mul_f32_e32 v79, v85, v98
	v_mul_f32_e32 v78, v111, v78
	v_mul_f32_e32 v88, v213, v88
	s_and_b64 vcc, exec, s[4:5]
	v_fmac_f32_e32 v99, 0x3f317217, v120
	v_cmp_lt_f32_e64 s[4:5], |v120|, s57
	v_cndmask_b32_e64 v115, 0, v225, s[0:1]
	v_exp_f32_e32 v80, v83
	v_exp_f32_e32 v83, v96
	v_min_f32_e64 v85, -v60, s60
	v_max_f32_e32 v96, 0xc2a00000, v60
	v_sub_f32_e32 v97, v97, v233
	v_fma_f32 v98, v116, s56, -v100
	v_ldexp_f32 v100, v118, v113
	v_fma_f32 v111, v213, v94, v208
	v_cvt_pk_bf16_f32 v79, v79, s0
	v_cvt_pk_bf16_f32 v78, v78, s0
	v_cmp_gt_f32_e64 s[0:1], s54, v110
	v_mul_f32_e32 v85, 0x3fb8aa3b, v85
	v_mul_f32_e32 v96, 0x3fb8aa3b, v96
	v_add_f32_e32 v60, v60, v97
	v_cndmask_b32_e64 v97, v120, v99, s[4:5]
	v_fmac_f32_e32 v98, 0x3377d1cf, v116
	v_mul_f32_e32 v99, 0x3f317217, v112
	v_log_f32_e32 v100, v100
	v_cndmask_b32_e64 v113, 0, 32, s[0:1]
	v_max_f32_e32 v111, 0xda24260, v111
	ds_write_b16 v61, v79 offset:5184
	ds_write_b16 v61, v78 offset:576
	v_mul_f32_e32 v78, v88, v81
	v_mul_f32_e32 v77, v82, v77
	v_sub_f32_e32 v84, 1.0, v84
	v_fmac_f32_e32 v98, 0x3f317217, v116
	v_cmp_lt_f32_e64 s[4:5], |v116|, s57
	v_cndmask_b32_e64 v117, 0, v225, s[0:1]
	v_exp_f32_e32 v79, v85
	v_exp_f32_e32 v81, v96
	v_min_f32_e64 v82, -v60, s60
	v_max_f32_e32 v85, 0xc2a00000, v60
	v_sub_f32_e32 v88, v97, v229
	v_fma_f32 v96, v112, s56, -v99
	v_ldexp_f32 v97, v110, v113
	v_cvt_pk_bf16_f32 v78, v78, s0
	v_cvt_pk_bf16_f32 v77, v77, s0
	v_cmp_gt_f32_e64 s[0:1], s54, v111
	v_mul_f32_e32 v84, v213, v84
	v_mul_f32_e32 v82, 0x3fb8aa3b, v82
	v_mul_f32_e32 v85, 0x3fb8aa3b, v85
	v_add_f32_e32 v60, v60, v88
	v_cndmask_b32_e64 v88, v116, v98, s[4:5]
	v_fmac_f32_e32 v96, 0x3377d1cf, v112
; __device__ __forceinline__ bf16_t f2bf(float f) { return (bf16_t)(cvt_pk_bf16(f, 0.f) & 0xffffu); }
; __device__ __forceinline__ float bf2f(bf16_t b) { return __uint_as_float(((unsigned)b) << 16); }
; __device__ __forceinline__ float sigmoidf_(float x) { return 1.0f / (1.0f + __expf(-x)); }
; template <int MODE>
; __device__ __forceinline__ void hgrn_mfma(const Ctx& C, int l, int z, int b, int hd, int c, f32x4 (&Sacc)[4][4], float& dectot, unsigned char* wl, float lb) {
;     ...
;             for (int t = 0; t < 16; ++t) {
;                 const float fl = bf2f(fv[t]);
;                 const float sg = sigmoidf_(fl);
;                 const float f = lb + (1.0f - lb) * sg, kk = (1.0f - lb) * (1.0f - sg);
;                 bacc += __logf(fmaxf(f, 1e-30f));
;                 Kb[(g8 * 16 + t) * HPT + lane] = f2bf(kk * __expf(fminf(-bacc, 80.f)));
;                 if (MODE != 0) Qt[(g8 * 16 + t) * HPT + lane] = f2bf(bf2f(qv[t]) * __expf(fmaxf(bacc, -80.f)));
;                 Vv[(g8 * 16 + t) * HPT + lane] = vv[t];
;             }
	v_mul_f32_e32 v98, 0x3f317217, v101
	v_log_f32_e32 v97, v97
	v_cndmask_b32_e64 v99, 0, 32, s[0:1]
	v_sub_f32_e32 v86, 1.0, v86
	v_fmac_f32_e32 v96, 0x3f317217, v112
	v_cmp_lt_f32_e64 s[4:5], |v112|, s57
	ds_write_b16 v61, v78 offset:5328
	ds_write_b16 v61, v77 offset:720
	v_mul_f32_e32 v77, v84, v80
	v_mul_f32_e32 v74, v83, v74
	v_exp_f32_e32 v78, v82
	v_exp_f32_e32 v80, v85
	v_min_f32_e64 v82, -v60, s60
	v_max_f32_e32 v83, 0xc2a00000, v60
	v_sub_f32_e32 v84, v88, v190
	v_fma_f32 v85, v101, s56, -v98
	v_ldexp_f32 v88, v111, v99
	v_mul_f32_e32 v86, v213, v86
	v_cvt_pk_bf16_f32 v77, v77, s0
	v_cvt_pk_bf16_f32 v74, v74, s0
	v_mul_f32_e32 v82, 0x3fb8aa3b, v82
	v_mul_f32_e32 v83, 0x3fb8aa3b, v83
	v_add_f32_e32 v60, v60, v84
	v_cndmask_b32_e64 v84, v112, v96, s[4:5]
	v_fmac_f32_e32 v85, 0x3377d1cf, v101
	v_mul_f32_e32 v96, 0x3f317217, v100
	v_log_f32_e32 v88, v88
	v_sub_f32_e32 v87, 1.0, v87
	v_cndmask_b32_e64 v110, 0, v225, s[0:1]
	v_fmac_f32_e32 v85, 0x3f317217, v101
	v_cmp_lt_f32_e64 s[0:1], |v101|, s57
	ds_write_b16 v61, v77 offset:5472
	ds_write_b16 v61, v74 offset:864
	v_mul_f32_e32 v74, v86, v79
	v_mul_f32_e32 v72, v81, v72
	v_exp_f32_e32 v77, v82
	v_exp_f32_e32 v79, v83
	v_min_f32_e64 v81, -v60, s60
	v_max_f32_e32 v82, 0xc2a00000, v60
	v_sub_f32_e32 v83, v84, v126
	v_fma_f32 v84, v100, s56, -v96
	v_mul_f32_e32 v87, v213, v87
	v_cvt_pk_bf16_f32 v74, v74, s0
	v_cvt_pk_bf16_f32 v72, v72, s0
	v_mul_f32_e32 v81, 0x3fb8aa3b, v81
	v_mul_f32_e32 v82, 0x3fb8aa3b, v82
	v_add_f32_e32 v60, v60, v83
	v_cndmask_b32_e64 v83, v101, v85, s[0:1]
	v_fmac_f32_e32 v84, 0x3377d1cf, v100
	v_mul_f32_e32 v85, 0x3f317217, v97
	v_sub_f32_e32 v89, 1.0, v89
	v_fmac_f32_e32 v84, 0x3f317217, v100
	v_cmp_lt_f32_e64 s[0:1], |v100|, s57
	ds_write_b16 v61, v74 offset:5616
	ds_write_b16 v61, v72 offset:1008
	v_mul_f32_e32 v72, v87, v78
	v_mul_f32_e32 v71, v80, v71
	v_exp_f32_e32 v74, v81
	v_exp_f32_e32 v78, v82
	v_min_f32_e64 v80, -v60, s60
	v_max_f32_e32 v81, 0xc2a00000, v60
	v_sub_f32_e32 v82, v83, v114
	v_fma_f32 v83, v97, s56, -v85
	v_mul_f32_e32 v89, v213, v89
	v_cvt_pk_bf16_f32 v72, v72, s0
	v_cvt_pk_bf16_f32 v71, v71, s0
	v_mul_f32_e32 v80, 0x3fb8aa3b, v80
	v_mul_f32_e32 v81, 0x3fb8aa3b, v81
	v_add_f32_e32 v60, v60, v82
	v_cndmask_b32_e64 v82, v100, v84, s[0:1]
	v_fmac_f32_e32 v83, 0x3377d1cf, v97
	v_mul_f32_e32 v84, 0x3f317217, v88
	v_sub_f32_e32 v90, 1.0, v90
	v_fmac_f32_e32 v83, 0x3f317217, v97
	v_cmp_lt_f32_e64 s[0:1], |v97|, s57
	ds_write_b16 v61, v72 offset:5760
	ds_write_b16 v61, v71 offset:1152
	v_mul_f32_e32 v71, v89, v77
	v_mul_f32_e32 v64, v79, v64
	v_exp_f32_e32 v72, v80
	v_exp_f32_e32 v77, v81
	v_min_f32_e64 v79, -v60, s60
	v_max_f32_e32 v80, 0xc2a00000, v60
	v_sub_f32_e32 v81, v82, v115
	v_fma_f32 v82, v88, s56, -v84
	v_mul_f32_e32 v90, v213, v90
	v_cvt_pk_bf16_f32 v71, v71, s0
	v_cvt_pk_bf16_f32 v64, v64, s0
	v_mul_f32_e32 v79, 0x3fb8aa3b, v79
	v_mul_f32_e32 v80, 0x3fb8aa3b, v80
	v_add_f32_e32 v60, v60, v81
	v_cndmask_b32_e64 v81, v97, v83, s[0:1]
	v_fmac_f32_e32 v82, 0x3377d1cf, v88
	v_sub_f32_e32 v92, 1.0, v92
	v_fmac_f32_e32 v82, 0x3f317217, v88
	v_cmp_lt_f32_e64 s[0:1], |v88|, s57
	ds_write_b16 v61, v71 offset:5904
	ds_write_b16 v61, v64 offset:1296
	v_mul_f32_e32 v64, v90, v74
	v_mul_f32_e32 v62, v78, v62
	v_exp_f32_e32 v71, v79
	v_exp_f32_e32 v74, v80
	v_min_f32_e64 v78, -v60, s60
	v_max_f32_e32 v79, 0xc2a00000, v60
	v_sub_f32_e32 v80, v81, v117
	v_mul_f32_e32 v92, v213, v92
	v_cvt_pk_bf16_f32 v64, v64, s0
	v_cvt_pk_bf16_f32 v62, v62, s0
	v_mul_f32_e32 v78, 0x3fb8aa3b, v78
	v_mul_f32_e32 v79, 0x3fb8aa3b, v79
	v_add_f32_e32 v60, v60, v80
	v_cndmask_b32_e64 v80, v88, v82, s[0:1]
	v_sub_f32_e32 v91, 1.0, v91
	ds_write_b16 v61, v64 offset:6048
	ds_write_b16 v61, v62 offset:1440
	v_mul_f32_e32 v62, v92, v72
	v_mul_f32_e32 v63, v77, v63
	v_exp_f32_e32 v64, v78
	v_exp_f32_e32 v72, v79
	v_min_f32_e64 v77, -v60, s60
	v_sub_f32_e32 v79, v80, v110
	v_mul_f32_e32 v91, v213, v91
	v_max_f32_e32 v78, 0xc2a00000, v60
	v_cvt_pk_bf16_f32 v62, v62, s0
	v_cvt_pk_bf16_f32 v63, v63, s0
	v_mul_f32_e32 v77, 0x3fb8aa3b, v77
	v_add_f32_e32 v60, v60, v79
	v_sub_f32_e32 v93, 1.0, v93
	v_mul_f32_e32 v78, 0x3fb8aa3b, v78
	ds_write_b16 v61, v62 offset:6192
	ds_write_b16 v61, v63 offset:1584
	v_mul_f32_e32 v62, v91, v71
	v_mul_f32_e32 v63, v74, v70
	v_exp_f32_e32 v70, v77
	v_min_f32_e64 v74, -v60, s60
	v_mul_f32_e32 v93, v213, v93
	v_exp_f32_e32 v71, v78
	v_max_f32_e32 v77, 0xc2a00000, v60
	v_cvt_pk_bf16_f32 v62, v62, s0
	v_mul_f32_e32 v74, 0x3fb8aa3b, v74
	v_sub_f32_e32 v95, 1.0, v95
	v_cvt_pk_bf16_f32 v63, v63, s0
	v_mul_f32_e32 v77, 0x3fb8aa3b, v77
	ds_write_b16 v61, v62 offset:6336
	ds_write_b16 v61, v63 offset:1728
	v_mul_f32_e32 v62, v93, v64
	v_exp_f32_e32 v64, v74
	v_mul_f32_e32 v95, v213, v95
	v_mul_f32_e32 v63, v72, v73
	v_exp_f32_e32 v72, v77
	v_cvt_pk_bf16_f32 v62, v62, s0
	v_sub_f32_e32 v94, 1.0, v94
	v_cvt_pk_bf16_f32 v63, v63, s0
	ds_write_b16 v61, v62 offset:6480
	ds_write_b16 v61, v63 offset:1872
	v_mul_f32_e32 v62, v95, v70
	v_mul_f32_e32 v94, v213, v94
	v_mul_f32_e32 v63, v71, v75
	v_cvt_pk_bf16_f32 v62, v62, s0
	v_cvt_pk_bf16_f32 v63, v63, s0
	ds_write_b16 v61, v62 offset:6624
	ds_write_b16 v61, v63 offset:2016
	v_mul_f32_e32 v62, v94, v64
	v_mul_f32_e32 v63, v72, v76
	v_cvt_pk_bf16_f32 v62, v62, s0
	v_cvt_pk_bf16_f32 v63, v63, s0
	ds_write_b16 v61, v62 offset:6768
	ds_write_b16 v61, v63 offset:2160
	s_cbranch_vccz .LBB0_743
; template <int MODE>
; __device__ __forceinline__ void hgrn_mfma(const Ctx& C, int l, int z, int b, int hd, int c, f32x4 (&Sacc)[4][4], float& dectot, unsigned char* wl, float lb) {
;     ...
;         { const float eb = __expf(bacc); dl[lane] = eb; dectot *= eb; }
;         wave_lds_fence();
;         f32x4 Oacc[2][4];
;         if (MODE != 0) {
;             bf16x8 Sb[2][4];
; #pragma unroll
;             for (int ks = 0; ks < 2; ++ks)
; #pragma unroll
;                 for (int vt = 0; vt < 4; ++vt) { union { bf16x8 v; unsigned u[4]; } t_;
;                     t_.u[0] = cvt_pk_bf16(Sacc[2 * ks][vt][0], Sacc[2 * ks][vt][1]); t_.u[1] = cvt_pk_bf16(Sacc[2 * ks][vt][2], Sacc[2 * ks][vt][3]);
;                     t_.u[2] = cvt_pk_bf16(Sacc[2 * ks + 1][vt][0], Sacc[2 * ks + 1][vt][1]); t_.u[3] = cvt_pk_bf16(Sacc[2 * ks + 1][vt][2], Sacc[2 * ks + 1][vt][3]); Sb[ks][vt] = t_.v; }
;             float zz = 0.f; asm volatile("" : "+v"(zz));
; #pragma unroll
;             for (int tt = 0; tt < 2; ++tt)
; #pragma unroll
;                 for (int vt = 0; vt < 4; ++vt) Oacc[tt][vt] = (f32x4){zz, zz, zz, zz};
; #pragma unroll
;             for (int tt = 0; tt < 2; ++tt)
; #pragma unroll
;                 for (int ks = 0; ks < 2; ++ks) { const bf16_t* qp = Qt + (16 * tt + fr) * HPT + 32 * ks + 4 * quad;
;                     union { bf16x8 v; u32x2 h[2]; } a_; a_.h[0] = *(const u32x2*)qp; a_.h[1] = *(const u32x2*)(qp + 16);
; #pragma unroll
;                     for (int vt = 0; vt < 4; ++vt) Oacc[tt][vt] = __builtin_amdgcn_mfma_f32_16x16x32_bf16(a_.v, Sb[ks][vt], Oacc[tt][vt], 0, 0, 0); }
;             f32x4 P00 = {zz, zz, zz, zz}, P01 = {zz, zz, zz, zz}, P11 = {zz, zz, zz, zz};
; #pragma unroll
;             for (int ks = 0; ks < 2; ++ks) {
;                 const bf16x8 kA0 = *(const bf16x8*)(Kb + fr * HPT + 32 * ks + 8 * quad), kA1 = *(const bf16x8*)(Kb + (16 + fr) * HPT + 32 * ks + 8 * quad);
;                 const bf16x8 qB0 = *(const bf16x8*)(Qt + fr * HPT + 32 * ks + 8 * quad), qB1 = *(const bf16x8*)(Qt + (16 + fr) * HPT + 32 * ks + 8 * quad);
;                 P00 = __builtin_amdgcn_mfma_f32_16x16x32_bf16(kA0, qB0, P00, 0, 0, 0);
;                 P01 = __builtin_amdgcn_mfma_f32_16x16x32_bf16(kA0, qB1, P01, 0, 0, 0);
;                 P11 = __builtin_amdgcn_mfma_f32_16x16x32_bf16(kA1, qB1, P11, 0, 0, 0);
;             }
; #pragma unroll
	v_mul_f32_e32 v60, 0x3fb8aa3b, v60
	v_exp_f32_e32 v60, v60
	v_mov_b32_e32 v98, v65
	v_cvt_pk_bf16_f32 v61, v2, v3
	v_cvt_pk_bf16_f32 v62, v16, v17
	ds_write_b32 v134, v60 offset:13824
	s_waitcnt lgkmcnt(0)
	ds_read2_b64 v[110:113], v141 offset1:4
	ds_read2_b64 v[126:129], v141 offset0:8 offset1:12
	v_cvt_pk_bf16_f32 v60, v0, v1
	v_cvt_pk_bf16_f32 v63, v18, v19
	v_cvt_pk_bf16_f32 v70, v4, v5
	v_cvt_pk_bf16_f32 v71, v6, v7
	v_cvt_pk_bf16_f32 v72, v20, v21
	v_cvt_pk_bf16_f32 v73, v22, v23
	v_cvt_pk_bf16_f32 v78, v8, v9
	v_cvt_pk_bf16_f32 v79, v10, v11
	v_cvt_pk_bf16_f32 v80, v24, v25
	v_cvt_pk_bf16_f32 v81, v26, v27
	v_cvt_pk_bf16_f32 v86, v12, v13
	v_cvt_pk_bf16_f32 v87, v14, v15
	v_cvt_pk_bf16_f32 v88, v28, v29
	v_cvt_pk_bf16_f32 v89, v30, v31
	v_mov_b32_e32 v99, v98
	v_mov_b32_e32 v100, v98
	v_mov_b32_e32 v101, v98
	v_cvt_pk_bf16_f32 v74, v32, v33
	v_cvt_pk_bf16_f32 v75, v34, v35
	s_waitcnt lgkmcnt(1)
	v_mfma_f32_16x16x32_bf16 v[114:117], v[110:113], v[60:63], v[98:101]
	v_cvt_pk_bf16_f32 v76, v48, v49
	v_cvt_pk_bf16_f32 v77, v50, v51
	v_cvt_pk_bf16_f32 v82, v36, v37
	v_mfma_f32_16x16x32_bf16 v[118:121], v[110:113], v[70:73], v[98:101]
	v_cvt_pk_bf16_f32 v83, v38, v39
	v_cvt_pk_bf16_f32 v84, v52, v53
	v_cvt_pk_bf16_f32 v85, v54, v55
	v_mfma_f32_16x16x32_bf16 v[122:125], v[110:113], v[78:81], v[98:101]
	v_cvt_pk_bf16_f32 v90, v40, v41
	v_cvt_pk_bf16_f32 v91, v42, v43
	v_cvt_pk_bf16_f32 v92, v56, v57
	v_mfma_f32_16x16x32_bf16 v[110:113], v[110:113], v[86:89], v[98:101]
	v_cvt_pk_bf16_f32 v93, v58, v59
	v_cvt_pk_bf16_f32 v94, v44, v45
	v_cvt_pk_bf16_f32 v95, v46, v47
	v_cvt_pk_bf16_f32 v96, v66, v67
	v_cvt_pk_bf16_f32 v97, v68, v69
	v_add_u32_e32 v64, 0x800, v141
	s_waitcnt lgkmcnt(0)
	v_mfma_f32_16x16x32_bf16 v[114:117], v[126:129], v[74:77], v[114:117]
	s_add_i32 s36, s36, 1
	s_cmp_eq_u32 s36, 4
	v_mfma_f32_16x16x32_bf16 v[118:121], v[126:129], v[82:85], v[118:121]
	v_mfma_f32_16x16x32_bf16 v[122:125], v[126:129], v[90:93], v[122:125]
	v_mfma_f32_16x16x32_bf16 v[110:113], v[126:129], v[94:97], v[110:113]
	ds_read2_b64 v[126:129], v64 offset0:32 offset1:36
	s_waitcnt lgkmcnt(0)
	v_mfma_f32_16x16x32_bf16 v[60:63], v[126:129], v[60:63], v[98:101]
	v_mfma_f32_16x16x32_bf16 v[70:73], v[126:129], v[70:73], v[98:101]
	v_mfma_f32_16x16x32_bf16 v[78:81], v[126:129], v[78:81], v[98:101]
	v_mfma_f32_16x16x32_bf16 v[86:89], v[126:129], v[86:89], v[98:101]
	ds_read2_b64 v[126:129], v64 offset0:40 offset1:44
	s_waitcnt lgkmcnt(0)
	v_mfma_f32_16x16x32_bf16 v[74:77], v[126:129], v[74:77], v[60:63]
	v_mfma_f32_16x16x32_bf16 v[178:181], v[126:129], v[82:85], v[70:73]
	v_mfma_f32_16x16x32_bf16 v[78:81], v[126:129], v[90:93], v[78:81]
	v_mfma_f32_16x16x32_bf16 v[126:129], v[126:129], v[94:97], v[86:89]
	ds_read_b128 v[60:63], v138 offset:4608
	ds_read_b128 v[70:73], v138 offset:6912
	ds_read_b128 v[82:85], v138
	ds_read_b128 v[86:89], v138 offset:2304
	ds_read_b128 v[90:93], v138 offset:4672
	ds_read_b128 v[94:97], v138 offset:6976
	ds_read_b128 v[188:191], v138 offset:64
	ds_read_b128 v[230:233], v138 offset:2368
	s_waitcnt lgkmcnt(5)
	v_mfma_f32_16x16x32_bf16 v[82:85], v[60:63], v[82:85], v[98:101]
	s_waitcnt lgkmcnt(4)
	v_mfma_f32_16x16x32_bf16 v[70:73], v[70:73], v[86:89], v[98:101]
	s_waitcnt lgkmcnt(1)
	v_mfma_f32_16x16x32_bf16 v[82:85], v[90:93], v[188:191], v[82:85]
	s_waitcnt lgkmcnt(0)
	v_mfma_f32_16x16x32_bf16 v[70:73], v[94:97], v[230:233], v[70:73]
	v_mfma_f32_16x16x32_bf16 v[60:63], v[60:63], v[86:89], v[98:101]
	s_nop 4
	v_cndmask_b32_e64 v64, v85, 0, s[42:43]
	s_nop 0
	v_cndmask_b32_e64 v85, v73, 0, s[42:43]
	v_cndmask_b32_e64 v94, v72, 0, s[46:47]
	v_cndmask_b32_e64 v95, v71, 0, s[48:49]
	v_cndmask_b32_e64 v96, v70, 0, s[50:51]
	v_mfma_f32_16x16x32_bf16 v[70:73], v[90:93], v[230:233], v[60:63]
	v_cndmask_b32_e64 v84, v84, 0, s[46:47]
	v_cndmask_b32_e64 v83, v83, 0, s[48:49]
	v_cndmask_b32_e64 v82, v82, 0, s[50:51]
	v_cvt_pk_bf16_f32 v62, v82, v83
	v_cvt_pk_bf16_f32 v63, v84, v64
	v_mov_b32_e32 v64, v65
	s_nop 1
	v_cvt_pk_bf16_f32 v98, v70, v71
	v_cvt_pk_bf16_f32 v99, v72, v73
	ds_read_b64_tr_b16 v[72:73], v139 offset:11520
	ds_read_b64_tr_b16 v[70:71], v139 offset:9216
	ds_read_b64_tr_b16 v[90:91], v139 offset:9248
	v_cvt_pk_bf16_f32 v100, v96, v95
	v_cvt_pk_bf16_f32 v101, v94, v85
	s_waitcnt lgkmcnt(1)
	v_mfma_f32_16x16x32_bf16 v[82:85], v[62:65], v[70:73], v[114:117]
	ds_read_b64_tr_b16 v[92:93], v139 offset:11552
	ds_read_b64_tr_b16 v[94:95], v139 offset:9280
	ds_read_b64_tr_b16 v[96:97], v139 offset:11584
	ds_read_b64_tr_b16 v[114:115], v139 offset:9312
	ds_read_b64_tr_b16 v[116:117], v139 offset:11616
	v_mfma_f32_16x16x32_bf16 v[70:73], v[98:101], v[70:73], v[74:77]
	s_waitcnt lgkmcnt(4)
	v_mfma_f32_16x16x32_bf16 v[86:89], v[62:65], v[90:93], v[118:121]
	v_mfma_f32_16x16x32_bf16 v[74:77], v[98:101], v[90:93], v[178:181]
	s_waitcnt lgkmcnt(2)
	v_mfma_f32_16x16x32_bf16 v[90:93], v[62:65], v[94:97], v[122:125]
	v_mfma_f32_16x16x32_bf16 v[78:81], v[98:101], v[94:97], v[78:81]
	s_waitcnt lgkmcnt(0)
	v_mfma_f32_16x16x32_bf16 v[94:97], v[62:65], v[114:117], v[110:113]
	v_add_u32_e32 v64, v137, v136
	v_mfma_f32_16x16x32_bf16 v[60:63], v[98:101], v[114:117], v[126:129]
	ds_read_b64_tr_b16 v[98:99], v140 offset:9216
	ds_read_b64_tr_b16 v[100:101], v140 offset:9792
	ds_read_b64_tr_b16 v[110:111], v140 offset:9248
	ds_read_b64_tr_b16 v[112:113], v140 offset:9824
	ds_read_b64_tr_b16 v[114:115], v140 offset:9280
	ds_read_b64_tr_b16 v[116:117], v140 offset:9856
	ds_read_b64_tr_b16 v[118:119], v140 offset:9312
	ds_read_b64_tr_b16 v[120:121], v140 offset:9888
	ds_read_b64_tr_b16 v[124:125], v140 offset:5184
	ds_read_b64_tr_b16 v[122:123], v140 offset:4608
	ds_read_b64_tr_b16 v[126:127], v140 offset:4640
	ds_read_b128 v[128:131], v64 offset:13824
	s_waitcnt lgkmcnt(2)
; template <int MODE>
; __device__ __forceinline__ void hgrn_mfma(const Ctx& C, int l, int z, int b, int hd, int c, f32x4 (&Sacc)[4][4], float& dectot, unsigned char* wl, float lb) {
;     ...
;         {
;             bf16x8 vB[4];
; #pragma unroll
;             for (int vt = 0; vt < 4; ++vt) { const bf16_t* vp = Vv + (8 * quad + (fr >> 2)) * HPT + 16 * vt + 4 * (fr & 3);
;                 union { bf16x8 v; s16x4 h[2]; } vb; vb.h[0] = lds_tr(vp); vb.h[1] = lds_tr(vp + 4 * HPT); vB[vt] = vb.v; }
; #pragma unroll
;             for (int kt = 0; kt < 4; ++kt) { const bf16_t* kp = Kb + (8 * quad + (fr >> 2)) * HPT + 16 * kt + 4 * (fr & 3);
;                 union { bf16x8 v; s16x4 h[2]; } ka; ka.h[0] = lds_tr(kp); ka.h[1] = lds_tr(kp + 4 * HPT);
;                 const f32x4 d4 = *(const f32x4*)(dl + 16 * kt + 4 * quad);
; #pragma unroll
;                 for (int vt = 0; vt < 4; ++vt) { Sacc[kt][vt] = __builtin_amdgcn_mfma_f32_16x16x32_bf16(ka.v, vB[vt], Sacc[kt][vt], 0, 0, 0); Sacc[kt][vt] *= d4; } }
;         }
;     ...
;         if (MODE == 2) {
; #pragma unroll
;             for (int tt = 0; tt < 2; ++tt) {
;                 bf16_t tmpv[4][4], gtv[4][4];
; #pragma unroll
;                 for (int r = 0; r < 4; ++r) { const int st = c * 128 + sc * 32 + 16 * tt + 4 * quad + r; const int tq = z ? 4095 - st : st;
;                     const size_t tok = (size_t)(b * SEQ + tq); const bf16_t* yp = ya + tok * 256 + hd * 64 + fr; const bf16_t* gp = pa + tok * 1280 + 1024 + hd * 64 + fr;
; #pragma unroll
;                     for (int vt = 0; vt < 4; ++vt) { tmpv[r][vt] = yp[16 * vt]; gtv[r][vt] = gp[16 * vt]; } }
	v_mfma_f32_16x16x32_bf16 v[0:3], v[122:125], v[98:101], v[0:3]
	v_mfma_f32_16x16x32_bf16 v[4:7], v[122:125], v[110:113], v[4:7]
	s_waitcnt lgkmcnt(0)
	s_nop 5
	v_pk_mul_f32 v[0:1], v[128:129], v[0:1]
	v_pk_mul_f32 v[2:3], v[130:131], v[2:3]
	v_mfma_f32_16x16x32_bf16 v[8:11], v[122:125], v[114:117], v[8:11]
	v_mfma_f32_16x16x32_bf16 v[12:15], v[122:125], v[118:121], v[12:15]
	v_mul_f32_e64 v4, v128, v4
	v_mul_f32_e64 v5, v129, v5
	s_nop 4
	v_pk_mul_f32 v[8:9], v[128:129], v[8:9]
	v_pk_mul_f32 v[6:7], v[130:131], v[6:7]
	v_pk_mul_f32 v[10:11], v[130:131], v[10:11]
	v_pk_mul_f32 v[12:13], v[128:129], v[12:13]
	ds_read_b64_tr_b16 v[128:129], v140 offset:5216
	ds_read_b128 v[122:125], v64 offset:13888
	s_waitcnt lgkmcnt(1)
	v_mfma_f32_16x16x32_bf16 v[16:19], v[126:129], v[98:101], v[16:19]
	v_mul_f32_e64 v14, v130, v14
	v_mul_f32_e64 v15, v131, v15
	v_mfma_f32_16x16x32_bf16 v[20:23], v[126:129], v[110:113], v[20:23]
	s_waitcnt lgkmcnt(0)
	s_nop 3
	v_pk_mul_f32 v[18:19], v[124:125], v[18:19]
	v_pk_mul_f32 v[16:17], v[122:123], v[16:17]
	v_mfma_f32_16x16x32_bf16 v[24:27], v[126:129], v[114:117], v[24:27]
	v_mfma_f32_16x16x32_bf16 v[28:31], v[126:129], v[118:121], v[28:31]
	v_mul_f32_e64 v22, v124, v22
	v_mul_f32_e64 v23, v125, v23
	v_pk_mul_f32 v[20:21], v[122:123], v[20:21]
	s_nop 3
	v_pk_mul_f32 v[26:27], v[124:125], v[26:27]
	v_pk_mul_f32 v[24:25], v[122:123], v[24:25]
	v_pk_mul_f32 v[30:31], v[124:125], v[30:31]
	v_pk_mul_f32 v[28:29], v[122:123], v[28:29]
	ds_read_b64_tr_b16 v[122:123], v140 offset:4672
	ds_read_b64_tr_b16 v[124:125], v140 offset:5248
	ds_read_b128 v[126:129], v64 offset:13952
	s_waitcnt lgkmcnt(1)
	v_mfma_f32_16x16x32_bf16 v[32:35], v[122:125], v[98:101], v[32:35]
	v_mfma_f32_16x16x32_bf16 v[36:39], v[122:125], v[110:113], v[36:39]
	s_waitcnt lgkmcnt(0)
	s_nop 5
	v_pk_mul_f32 v[34:35], v[128:129], v[34:35]
	v_pk_mul_f32 v[32:33], v[126:127], v[32:33]
	v_mfma_f32_16x16x32_bf16 v[40:43], v[122:125], v[114:117], v[40:43]
	v_mfma_f32_16x16x32_bf16 v[44:47], v[122:125], v[118:121], v[44:47]
	v_mul_f32_e64 v38, v128, v38
	v_mul_f32_e64 v39, v129, v39
	v_pk_mul_f32 v[36:37], v[126:127], v[36:37]
	s_nop 3
	v_pk_mul_f32 v[42:43], v[128:129], v[42:43]
	v_pk_mul_f32 v[40:41], v[126:127], v[40:41]
	v_pk_mul_f32 v[46:47], v[128:129], v[46:47]
	v_pk_mul_f32 v[44:45], v[126:127], v[44:45]
	ds_read_b64_tr_b16 v[122:123], v140 offset:4704
	ds_read_b64_tr_b16 v[124:125], v140 offset:5280
	ds_read_b128 v[126:129], v64 offset:14016
	s_waitcnt lgkmcnt(1)
	v_mfma_f32_16x16x32_bf16 v[48:51], v[122:125], v[98:101], v[48:51]
	v_and_b32_e32 v99, 64, v221
	v_xor_b32_e32 v64, 1, v221
	v_add_u32_e32 v99, 64, v99
	v_cmp_lt_i32_e32 vcc, v64, v99
	v_add_u32_e32 v98, s75, v214
	v_mfma_f32_16x16x32_bf16 v[56:59], v[122:125], v[114:117], v[56:59]
	v_cndmask_b32_e32 v64, v221, v64, vcc
	v_lshlrev_b32_e32 v231, 2, v64
	v_xor_b32_e32 v64, 2, v221
	v_cmp_lt_i32_e32 vcc, v64, v99
	v_mfma_f32_16x16x32_bf16 v[52:55], v[122:125], v[110:113], v[52:55]
	v_or_b32_e32 v116, 3, v98
	v_cndmask_b32_e32 v64, v221, v64, vcc
	v_lshlrev_b32_e32 v230, 2, v64
	v_xor_b32_e32 v64, 4, v221
	v_cmp_lt_i32_e32 vcc, v64, v99
	v_mfma_f32_16x16x32_bf16 v[66:69], v[122:125], v[118:121], v[66:69]
	v_ashrrev_i32_e32 v117, 31, v116
	v_cndmask_b32_e32 v64, v221, v64, vcc
	v_lshlrev_b32_e32 v229, 2, v64
	v_xor_b32_e32 v64, 8, v221
	v_cmp_lt_i32_e32 vcc, v64, v99
	v_ashrrev_i32_e32 v99, 31, v98
	v_lshlrev_b64 v[100:101], 9, v[98:99]
	v_lshl_add_u64 v[114:115], v[106:107], 0, v[100:101]
	v_or_b32_e32 v100, 1, v98
	v_ashrrev_i32_e32 v101, 31, v100
	v_lshlrev_b64 v[110:111], 9, v[100:101]
	v_mad_i64_i32 v[124:125], s[0:1], v100, s62, v[108:109]
	v_or_b32_e32 v100, 2, v98
	v_ashrrev_i32_e32 v101, 31, v100
	v_lshl_add_u64 v[112:113], v[106:107], 0, v[110:111]
	v_lshlrev_b64 v[110:111], 9, v[100:101]
	v_mad_i64_i32 v[120:121], s[0:1], v100, s62, v[108:109]
	v_lshlrev_b64 v[100:101], 9, v[116:117]
	s_waitcnt lgkmcnt(0)
	v_pk_mul_f32 v[48:49], v[126:127], v[48:49]
	v_pk_mul_f32 v[52:53], v[126:127], v[52:53]
	v_pk_mul_f32 v[56:57], v[126:127], v[56:57]
	v_pk_mul_f32 v[66:67], v[126:127], v[66:67]
	v_mad_i64_i32 v[126:127], s[0:1], v98, s62, v[108:109]
	v_lshl_add_u64 v[110:111], v[106:107], 0, v[110:111]
	v_lshl_add_u64 v[100:101], v[106:107], 0, v[100:101]
	global_load_ushort v118, v[114:115], off
	global_load_ushort v119, v[114:115], off offset:32
	global_load_ushort v130, v[114:115], off offset:64
	global_load_ushort v131, v[114:115], off offset:96
	global_load_ushort v244, v[112:113], off
	global_load_ushort v245, v[112:113], off offset:32
	global_load_ushort v242, v[112:113], off offset:64
	global_load_ushort v243, v[112:113], off offset:96
	global_load_ushort v237, v[110:111], off
	global_load_ushort v238, v[110:111], off offset:32
	global_load_ushort v235, v[110:111], off offset:64
	global_load_ushort v236, v[110:111], off offset:96
	global_load_ushort v233, v[100:101], off
	global_load_ushort v234, v[100:101], off offset:32
	global_load_ushort v99, v[100:101], off offset:64
	global_load_ushort v232, v[100:101], off offset:96
	v_mov_b32_e32 v122, v82
	global_load_ushort v82, v[126:127], off offset:2048
	global_load_ushort v178, v[126:127], off offset:2080
	global_load_ushort v179, v[126:127], off offset:2112
	global_load_ushort v180, v[126:127], off offset:2144
	v_mov_b32_e32 v123, v86
	v_cndmask_b32_e32 v64, v221, v64, vcc
	v_pk_mul_f32 v[50:51], v[128:129], v[50:51]
	v_pk_mul_f32 v[54:55], v[128:129], v[54:55]
	v_pk_mul_f32 v[58:59], v[128:129], v[58:59]
	v_pk_mul_f32 v[68:69], v[128:129], v[68:69]
	v_lshlrev_b32_e32 v64, 2, v64
	v_mad_i64_i32 v[116:117], s[0:1], v116, s62, v[108:109]
	s_waitcnt vmcnt(16)
; __device__ __forceinline__ bf16_t f2bf(float f) { return (bf16_t)(cvt_pk_bf16(f, 0.f) & 0xffffu); }
; __device__ __forceinline__ float bf2f(bf16_t b) { return __uint_as_float(((unsigned)b) << 16); }
; __device__ __forceinline__ float siluf_(float x) { return x * sigmoidf_(x); }
; template <int MODE>
; __device__ __forceinline__ void hgrn_mfma(const Ctx& C, int l, int z, int b, int hd, int c, f32x4 (&Sacc)[4][4], float& dectot, unsigned char* wl, float lb) {
;     ...
;                 for (int r = 0; r < 4; ++r) { const int st = c * 128 + sc * 32 + 16 * tt + 4 * quad + r; const int tq = z ? 4095 - st : st;
;                     bf16_t* yp = ya + (size_t)(b * SEQ + tq) * 256 + hd * 64 + fr;
;                     float o[4]; float ss = 0.f;
; #pragma unroll
;                     for (int vt = 0; vt < 4; ++vt) { o[vt] = Oacc[tt][vt][r] + bf2f(tmpv[r][vt]); ss += o[vt] * o[vt]; }
;                     ss += __shfl_xor(ss, 1); ss += __shfl_xor(ss, 2); ss += __shfl_xor(ss, 4); ss += __shfl_xor(ss, 8);
;                     const float rs = rsqrtf(ss * (1.f / 64.f) + 1e-6f);
; #pragma unroll
;                     for (int vt = 0; vt < 4; ++vt) yp[16 * vt] = f2bf(o[vt] * rs * gnv[vt] * siluf_(bf2f(gtv[r][vt]))); }
	v_lshlrev_b32_e32 v118, 16, v118
	s_waitcnt vmcnt(15)
	v_lshlrev_b32_e32 v119, 16, v119
	v_pk_add_f32 v[122:123], v[122:123], v[118:119]
	s_waitcnt vmcnt(14)
	v_lshlrev_b32_e32 v118, 16, v130
	v_mov_b32_e32 v130, v90
	s_waitcnt vmcnt(13)
	v_lshlrev_b32_e32 v119, 16, v131
	v_mov_b32_e32 v131, v94
	v_pk_mul_f32 v[128:129], v[122:123], v[122:123]
	s_waitcnt vmcnt(0)
	v_lshlrev_b32_e32 v82, 16, v82
	v_mul_f32_e32 v86, 0xbfb8aa3b, v82
	v_exp_f32_e32 v86, v86
	v_pk_add_f32 v[118:119], v[130:131], v[118:119]
	v_add_f32_e32 v86, 1.0, v86
	v_pk_mul_f32 v[130:131], v[118:119], v[118:119]
	v_rcp_f32_e32 v86, v86
	s_nop 0
	v_mul_f32_e32 v246, v86, v82
	v_lshlrev_b32_e32 v82, 16, v178
	v_mul_f32_e32 v86, 0xbfb8aa3b, v82
	v_exp_f32_e32 v86, v86
	s_nop 0
	v_add_f32_e32 v86, 1.0, v86
	s_nop 0
	v_rcp_f32_e32 v86, v86
	s_nop 0
	v_mul_f32_e32 v239, v86, v82
	v_lshlrev_b32_e32 v82, 16, v179
	v_mul_f32_e32 v86, 0xbfb8aa3b, v82
	v_exp_f32_e32 v86, v86
	s_nop 0
	v_add_f32_e32 v86, 1.0, v86
	s_nop 0
	v_rcp_f32_e32 v86, v86
	s_nop 0
	v_mul_f32_e32 v240, v86, v82
	v_lshlrev_b32_e32 v82, 16, v180
	v_mul_f32_e32 v86, 0xbfb8aa3b, v82
	v_exp_f32_e32 v86, v86
	s_nop 0
	v_add_f32_e32 v86, 1.0, v86
	s_nop 0
	v_rcp_f32_e32 v86, v86
	s_nop 0
	v_mul_f32_e32 v241, v86, v82
	v_lshlrev_b32_e32 v127, 16, v245
	v_lshlrev_b32_e32 v126, 16, v244
	v_mov_b32_e32 v86, v83
	v_pk_add_f32 v[126:127], v[86:87], v[126:127]
	v_lshlrev_b32_e32 v87, 16, v243
	v_lshlrev_b32_e32 v86, 16, v242
	v_mov_b32_e32 v94, v91
	v_pk_mul_f32 v[82:83], v[126:127], v[126:127]
	v_pk_add_f32 v[86:87], v[94:95], v[86:87]
	v_mov_b32_e32 v94, v82
	v_pk_mul_f32 v[90:91], v[86:87], v[86:87]
	v_mov_b32_e32 v95, v128
	v_mov_b32_e32 v128, v83
	v_pk_add_f32 v[82:83], v[94:95], v[128:129]
	v_mov_b32_e32 v94, v90
	v_mov_b32_e32 v95, v130
	v_pk_add_f32 v[82:83], v[82:83], v[94:95]
	v_mov_b32_e32 v130, v91
	v_pk_add_f32 v[82:83], v[82:83], v[130:131]
	ds_bpermute_b32 v91, v231, v83
	ds_bpermute_b32 v90, v231, v82
	s_waitcnt lgkmcnt(0)
	v_pk_add_f32 v[82:83], v[82:83], v[90:91]
	ds_bpermute_b32 v91, v230, v83
	ds_bpermute_b32 v90, v230, v82
	s_waitcnt lgkmcnt(0)
	v_pk_add_f32 v[82:83], v[82:83], v[90:91]
	ds_bpermute_b32 v91, v229, v83
	ds_bpermute_b32 v90, v229, v82
	s_waitcnt lgkmcnt(0)
	v_pk_add_f32 v[82:83], v[82:83], v[90:91]
	ds_bpermute_b32 v91, v64, v83
	ds_bpermute_b32 v90, v64, v82
	s_waitcnt lgkmcnt(0)
	v_pk_add_f32 v[90:91], v[82:83], v[90:91]
	v_mov_b64_e32 v[82:83], s[66:67]
	v_pk_fma_f32 v[90:91], v[90:91], s[2:3], v[82:83] op_sel_hi:[1,0,0]
	s_nop 0
	v_mul_f32_e32 v94, 0x4b800000, v91
	v_cmp_gt_f32_e64 s[0:1], s54, v91
	v_cmp_gt_f32_e32 vcc, s54, v90
	s_nop 0
	v_cndmask_b32_e64 v91, v91, v94, s[0:1]
	v_rsq_f32_e32 v91, v91
	s_nop 0
	v_mul_f32_e32 v94, 0x45800000, v91
	v_cndmask_b32_e64 v91, v91, v94, s[0:1]
	v_mul_f32_e32 v94, v122, v91
	global_load_ushort v95, v[124:125], off offset:2048
	global_load_ushort v128, v[124:125], off offset:2080
	global_load_ushort v129, v[124:125], off offset:2112
	global_load_ushort v130, v[124:125], off offset:2144
	global_load_ushort v131, v[120:121], off offset:2048
	global_load_ushort v178, v[120:121], off offset:2080
	s_nop 0
	global_load_ushort v125, v[120:121], off offset:2112
	global_load_ushort v124, v[120:121], off offset:2144
	global_load_ushort v122, v[116:117], off offset:2048
	s_nop 0
	global_load_ushort v121, v[116:117], off offset:2080
	global_load_ushort v120, v[116:117], off offset:2112
	s_nop 0
	global_load_ushort v116, v[116:117], off offset:2144
	v_mul_f32_e32 v94, v209, v94
	v_mul_f32_e32 v94, v246, v94
	v_cvt_pk_bf16_f32 v94, v94, s0
	global_store_short v[114:115], v94, off
	v_mul_f32_e32 v94, v123, v91
	v_mul_f32_e32 v94, v210, v94
	v_mul_f32_e32 v94, v239, v94
	v_cvt_pk_bf16_f32 v94, v94, s0
	global_store_short v[114:115], v94, off offset:32
	v_mul_f32_e32 v94, v118, v91
	v_mul_f32_e32 v94, v211, v94
	v_mul_f32_e32 v94, v240, v94
	v_cvt_pk_bf16_f32 v94, v94, s0
	global_store_short v[114:115], v94, off offset:64
	v_mul_f32_e32 v91, v119, v91
	v_mul_f32_e32 v91, v212, v91
	v_mul_f32_e32 v91, v241, v91
	v_cvt_pk_bf16_f32 v91, v91, s0
	global_store_short v[114:115], v91, off offset:96
	v_mul_f32_e32 v91, 0x4b800000, v90
	v_cndmask_b32_e32 v90, v90, v91, vcc
	v_rsq_f32_e32 v90, v90
	s_waitcnt vmcnt(15)
	v_lshlrev_b32_e32 v94, 16, v95
	v_mul_f32_e32 v95, 0xbfb8aa3b, v94
	v_exp_f32_e32 v95, v95
	v_mul_f32_e32 v91, 0x45800000, v90
	v_cndmask_b32_e32 v90, v90, v91, vcc
	v_mul_f32_e32 v91, v126, v90
	v_add_f32_e32 v95, 1.0, v95
	v_mul_f32_e32 v91, v209, v91
	v_mul_f32_e32 v86, v86, v90
	v_mul_f32_e32 v86, v211, v86
	v_rcp_f32_e32 v95, v95
	s_nop 0
	v_mul_f32_e32 v94, v95, v94
	v_mul_f32_e32 v91, v94, v91
	s_waitcnt vmcnt(14)
	v_lshlrev_b32_e32 v94, 16, v128
	v_mul_f32_e32 v95, 0xbfb8aa3b, v94
	v_exp_f32_e32 v95, v95
	v_cvt_pk_bf16_f32 v91, v91, s0
	global_store_short v[112:113], v91, off
	v_mul_f32_e32 v91, v127, v90
	v_add_f32_e32 v95, 1.0, v95
	v_mul_f32_e32 v91, v210, v91
	v_rcp_f32_e32 v95, v95
	s_nop 0
	v_mul_f32_e32 v94, v95, v94
	v_mul_f32_e32 v91, v94, v91
	v_cvt_pk_bf16_f32 v91, v91, s0
	global_store_short v[112:113], v91, off offset:32
	s_waitcnt vmcnt(15)
	v_lshlrev_b32_e32 v91, 16, v129
	v_mul_f32_e32 v94, 0xbfb8aa3b, v91
	v_exp_f32_e32 v94, v94
	s_nop 0
	v_add_f32_e32 v94, 1.0, v94
	s_nop 0
	v_rcp_f32_e32 v94, v94
	s_nop 0
	v_mul_f32_e32 v91, v94, v91
	v_mul_f32_e32 v86, v91, v86
	v_cvt_pk_bf16_f32 v86, v86, s0
	global_store_short v[112:113], v86, off offset:64
	v_mul_f32_e32 v86, v87, v90
	s_waitcnt vmcnt(15)
	v_lshlrev_b32_e32 v87, 16, v130
	v_mul_f32_e32 v90, 0xbfb8aa3b, v87
	v_exp_f32_e32 v90, v90
	v_mul_f32_e32 v86, v212, v86
	v_add_f32_e32 v90, 1.0, v90
	s_nop 0
	v_rcp_f32_e32 v90, v90
	s_nop 0
	v_mul_f32_e32 v87, v90, v87
	v_mov_b32_e32 v90, v84
	s_waitcnt vmcnt(14)
; __device__ __forceinline__ bf16_t f2bf(float f) { return (bf16_t)(cvt_pk_bf16(f, 0.f) & 0xffffu); }
; __device__ __forceinline__ float bf2f(bf16_t b) { return __uint_as_float(((unsigned)b) << 16); }
; __device__ __forceinline__ float siluf_(float x) { return x * sigmoidf_(x); }
; template <int MODE>
; __device__ __forceinline__ void hgrn_mfma(const Ctx& C, int l, int z, int b, int hd, int c, f32x4 (&Sacc)[4][4], float& dectot, unsigned char* wl, float lb) {
;     ...
;                 for (int r = 0; r < 4; ++r) { const int st = c * 128 + sc * 32 + 16 * tt + 4 * quad + r; const int tq = z ? 4095 - st : st;
;                     bf16_t* yp = ya + (size_t)(b * SEQ + tq) * 256 + hd * 64 + fr;
;                     float o[4]; float ss = 0.f;
; #pragma unroll
;                     for (int vt = 0; vt < 4; ++vt) { o[vt] = Oacc[tt][vt][r] + bf2f(tmpv[r][vt]); ss += o[vt] * o[vt]; }
;                     ss += __shfl_xor(ss, 1); ss += __shfl_xor(ss, 2); ss += __shfl_xor(ss, 4); ss += __shfl_xor(ss, 8);
;                     const float rs = rsqrtf(ss * (1.f / 64.f) + 1e-6f);
; #pragma unroll
;                     for (int vt = 0; vt < 4; ++vt) yp[16 * vt] = f2bf(o[vt] * rs * gnv[vt] * siluf_(bf2f(gtv[r][vt]))); }
	v_lshlrev_b32_e32 v84, 16, v131
	v_mov_b32_e32 v91, v88
	v_mul_f32_e32 v88, 0xbfb8aa3b, v84
	v_exp_f32_e32 v88, v88
	v_mul_f32_e32 v86, v87, v86
	v_cvt_pk_bf16_f32 v86, v86, s0
	v_mov_b32_e32 v94, v92
	v_add_f32_e32 v88, 1.0, v88
	v_mov_b32_e32 v95, v96
	global_store_short v[112:113], v86, off offset:96
	v_lshlrev_b32_e32 v87, 16, v238
	v_lshlrev_b32_e32 v86, 16, v237
	v_rcp_f32_e32 v88, v88
	s_nop 0
	v_mul_f32_e32 v117, v88, v84
	s_waitcnt vmcnt(14)
	v_lshlrev_b32_e32 v84, 16, v178
	v_mul_f32_e32 v88, 0xbfb8aa3b, v84
	v_exp_f32_e32 v88, v88
	v_pk_add_f32 v[90:91], v[90:91], v[86:87]
	v_lshlrev_b32_e32 v87, 16, v236
	v_lshlrev_b32_e32 v86, 16, v235
	v_add_f32_e32 v88, 1.0, v88
	v_pk_mul_f32 v[112:113], v[90:91], v[90:91]
	v_pk_add_f32 v[86:87], v[94:95], v[86:87]
	v_rcp_f32_e32 v88, v88
	s_nop 0
	v_mul_f32_e32 v118, v88, v84
	s_waitcnt vmcnt(13)
	v_lshlrev_b32_e32 v84, 16, v125
	v_mul_f32_e32 v88, 0xbfb8aa3b, v84
	v_exp_f32_e32 v88, v88
	v_pk_mul_f32 v[94:95], v[86:87], v[86:87]
	v_add_f32_e32 v88, 1.0, v88
	s_nop 0
	v_rcp_f32_e32 v88, v88
	s_nop 0
	v_mul_f32_e32 v119, v88, v84
	s_waitcnt vmcnt(12)
	v_lshlrev_b32_e32 v84, 16, v124
	v_mul_f32_e32 v88, 0xbfb8aa3b, v84
	v_exp_f32_e32 v88, v88
	s_nop 0
	v_add_f32_e32 v88, 1.0, v88
	s_nop 0
	v_rcp_f32_e32 v88, v88
	s_nop 0
	v_mul_f32_e32 v123, v88, v84
	v_lshlrev_b32_e32 v115, 16, v234
	v_lshlrev_b32_e32 v114, 16, v233
	v_mov_b32_e32 v88, v85
	v_pk_add_f32 v[88:89], v[88:89], v[114:115]
	v_lshlrev_b32_e32 v85, 16, v232
	v_lshlrev_b32_e32 v84, 16, v99
	v_mov_b32_e32 v96, v93
	v_pk_mul_f32 v[114:115], v[88:89], v[88:89]
	v_pk_add_f32 v[84:85], v[96:97], v[84:85]
	v_mov_b32_e32 v96, v114
	v_pk_mul_f32 v[92:93], v[84:85], v[84:85]
	v_mov_b32_e32 v97, v112
	v_mov_b32_e32 v112, v115
	v_pk_add_f32 v[96:97], v[96:97], v[112:113]
	v_mov_b32_e32 v112, v92
	v_mov_b32_e32 v113, v94
	v_pk_add_f32 v[96:97], v[96:97], v[112:113]
	v_mov_b32_e32 v94, v93
	v_pk_add_f32 v[92:93], v[96:97], v[94:95]
	ds_bpermute_b32 v95, v231, v93
	ds_bpermute_b32 v94, v231, v92
	v_mov_b32_e32 v99, v74
	s_waitcnt lgkmcnt(0)
	v_pk_add_f32 v[92:93], v[92:93], v[94:95]
	ds_bpermute_b32 v95, v230, v93
	ds_bpermute_b32 v94, v230, v92
	s_waitcnt lgkmcnt(0)
	v_pk_add_f32 v[92:93], v[92:93], v[94:95]
	ds_bpermute_b32 v95, v229, v93
	ds_bpermute_b32 v94, v229, v92
	s_waitcnt lgkmcnt(0)
	v_pk_add_f32 v[92:93], v[92:93], v[94:95]
	ds_bpermute_b32 v95, v64, v93
	ds_bpermute_b32 v94, v64, v92
	s_waitcnt lgkmcnt(0)
	v_pk_add_f32 v[92:93], v[92:93], v[94:95]
	s_nop 0
	v_pk_fma_f32 v[92:93], v[92:93], s[2:3], v[82:83] op_sel_hi:[1,0,0]
	s_nop 0
	v_mul_f32_e32 v94, 0x4b800000, v93
	v_cmp_gt_f32_e64 s[0:1], s54, v93
	v_cmp_gt_f32_e32 vcc, s54, v92
	s_nop 0
	v_cndmask_b32_e64 v93, v93, v94, s[0:1]
	v_rsq_f32_e32 v93, v93
	s_nop 0
	v_mul_f32_e32 v94, 0x45800000, v93
	v_cndmask_b32_e64 v93, v93, v94, s[0:1]
	v_mul_f32_e32 v86, v86, v93
	v_mul_f32_e32 v86, v211, v86
	v_mul_f32_e32 v86, v119, v86
	v_cvt_pk_bf16_f32 v86, v86, s0
	global_store_short v[110:111], v86, off offset:64
	v_mul_f32_e32 v86, v87, v93
	v_mul_f32_e32 v86, v212, v86
	v_mul_f32_e32 v86, v123, v86
	v_cvt_pk_bf16_f32 v86, v86, s0
	global_store_short v[110:111], v86, off offset:96
	v_mul_f32_e32 v86, 0x4b800000, v92
	v_mul_f32_e32 v90, v90, v93
	v_cndmask_b32_e32 v86, v92, v86, vcc
	v_mul_f32_e32 v90, v209, v90
	v_rsq_f32_e32 v86, v86
	v_mul_f32_e32 v90, v117, v90
	v_cvt_pk_bf16_f32 v90, v90, s0
	global_store_short v[110:111], v90, off
	v_mul_f32_e32 v90, v91, v93
	v_mul_f32_e32 v90, v210, v90
	v_mul_f32_e32 v87, 0x45800000, v86
	v_mul_f32_e32 v90, v118, v90
	v_cndmask_b32_e32 v86, v86, v87, vcc
	v_cvt_pk_bf16_f32 v90, v90, s0
	v_mul_f32_e32 v87, v88, v86
	s_waitcnt vmcnt(14)
	v_lshlrev_b32_e32 v88, 16, v122
	global_store_short v[110:111], v90, off offset:32
	v_mul_f32_e32 v90, 0xbfb8aa3b, v88
	v_exp_f32_e32 v90, v90
	v_mul_f32_e32 v87, v209, v87
	v_mul_f32_e32 v84, v84, v86
	v_mul_f32_e32 v84, v211, v84
	v_add_f32_e32 v90, 1.0, v90
	s_nop 0
	v_rcp_f32_e32 v90, v90
	s_nop 0
	v_mul_f32_e32 v88, v90, v88
	v_mul_f32_e32 v87, v88, v87
	v_cvt_pk_bf16_f32 v87, v87, s0
	s_waitcnt vmcnt(14)
	v_lshlrev_b32_e32 v88, 16, v121
	global_store_short v[100:101], v87, off
	v_mul_f32_e32 v87, v89, v86
	v_mul_f32_e32 v89, 0xbfb8aa3b, v88
	v_exp_f32_e32 v89, v89
	v_mul_f32_e32 v87, v210, v87
	v_add_f32_e32 v89, 1.0, v89
	s_nop 0
	v_rcp_f32_e32 v89, v89
	s_nop 0
	v_mul_f32_e32 v88, v89, v88
	v_mul_f32_e32 v87, v88, v87
	v_cvt_pk_bf16_f32 v87, v87, s0
	global_store_short v[100:101], v87, off offset:32
	s_waitcnt vmcnt(15)
	v_lshlrev_b32_e32 v87, 16, v120
	v_mul_f32_e32 v88, 0xbfb8aa3b, v87
	v_exp_f32_e32 v88, v88
	s_nop 0
	v_add_f32_e32 v88, 1.0, v88
	s_nop 0
	v_rcp_f32_e32 v88, v88
	s_nop 0
	v_mul_f32_e32 v87, v88, v87
	v_mul_f32_e32 v84, v87, v84
	v_cvt_pk_bf16_f32 v84, v84, s0
	global_store_short v[100:101], v84, off offset:64
	v_mul_f32_e32 v84, v85, v86
	s_waitcnt vmcnt(15)
; __device__ __forceinline__ bf16_t f2bf(float f) { return (bf16_t)(cvt_pk_bf16(f, 0.f) & 0xffffu); }
; __device__ __forceinline__ float bf2f(bf16_t b) { return __uint_as_float(((unsigned)b) << 16); }
; __device__ __forceinline__ float siluf_(float x) { return x * sigmoidf_(x); }
; template <int MODE>
; __device__ __forceinline__ void hgrn_mfma(const Ctx& C, int l, int z, int b, int hd, int c, f32x4 (&Sacc)[4][4], float& dectot, unsigned char* wl, float lb) {
;     ...
;                 for (int r = 0; r < 4; ++r) { const int st = c * 128 + sc * 32 + 16 * tt + 4 * quad + r; const int tq = z ? 4095 - st : st;
;                     const size_t tok = (size_t)(b * SEQ + tq); const bf16_t* yp = ya + tok * 256 + hd * 64 + fr; const bf16_t* gp = pa + tok * 1280 + 1024 + hd * 64 + fr;
; #pragma unroll
;                     for (int vt = 0; vt < 4; ++vt) { tmpv[r][vt] = yp[16 * vt]; gtv[r][vt] = gp[16 * vt]; } }
; #pragma unroll
;                 for (int r = 0; r < 4; ++r) { const int st = c * 128 + sc * 32 + 16 * tt + 4 * quad + r; const int tq = z ? 4095 - st : st;
;                     bf16_t* yp = ya + (size_t)(b * SEQ + tq) * 256 + hd * 64 + fr;
;                     float o[4]; float ss = 0.f;
; #pragma unroll
;                     for (int vt = 0; vt < 4; ++vt) { o[vt] = Oacc[tt][vt][r] + bf2f(tmpv[r][vt]); ss += o[vt] * o[vt]; }
;                     ss += __shfl_xor(ss, 1); ss += __shfl_xor(ss, 2); ss += __shfl_xor(ss, 4); ss += __shfl_xor(ss, 8);
;                     const float rs = rsqrtf(ss * (1.f / 64.f) + 1e-6f);
; #pragma unroll
;                     for (int vt = 0; vt < 4; ++vt) yp[16 * vt] = f2bf(o[vt] * rs * gnv[vt] * siluf_(bf2f(gtv[r][vt]))); }
	v_lshlrev_b32_e32 v85, 16, v116
	v_mul_f32_e32 v86, 0xbfb8aa3b, v85
	v_exp_f32_e32 v86, v86
	v_mul_f32_e32 v84, v212, v84
	v_or_b32_e32 v92, 19, v98
	v_ashrrev_i32_e32 v93, 31, v92
	v_add_f32_e32 v86, 1.0, v86
	s_nop 0
	v_rcp_f32_e32 v86, v86
	s_nop 0
	v_mul_f32_e32 v85, v86, v85
	v_mul_f32_e32 v84, v85, v84
	v_cvt_pk_bf16_f32 v84, v84, s0
	global_store_short v[100:101], v84, off offset:96
	v_or_b32_e32 v84, 16, v98
	v_ashrrev_i32_e32 v85, 31, v84
	v_lshlrev_b64 v[86:87], 9, v[84:85]
	v_lshl_add_u64 v[90:91], v[106:107], 0, v[86:87]
	global_load_ushort v94, v[90:91], off
	global_load_ushort v95, v[90:91], off offset:32
	global_load_ushort v114, v[90:91], off offset:64
	global_load_ushort v115, v[90:91], off offset:96
	v_mad_i64_i32 v[110:111], s[0:1], v84, s62, v[108:109]
	v_or_b32_e32 v84, 17, v98
	v_ashrrev_i32_e32 v85, 31, v84
	v_lshlrev_b64 v[86:87], 9, v[84:85]
	v_mad_i64_i32 v[100:101], s[0:1], v84, s62, v[108:109]
	v_or_b32_e32 v84, 18, v98
	v_ashrrev_i32_e32 v85, 31, v84
	v_lshl_add_u64 v[88:89], v[106:107], 0, v[86:87]
	v_lshlrev_b64 v[86:87], 9, v[84:85]
	v_mad_i64_i32 v[96:97], s[0:1], v84, s62, v[108:109]
	v_lshlrev_b64 v[84:85], 9, v[92:93]
	v_lshl_add_u64 v[86:87], v[106:107], 0, v[86:87]
	v_lshl_add_u64 v[84:85], v[106:107], 0, v[84:85]
	v_mov_b32_e32 v98, v70
	global_load_ushort v127, v[88:89], off
	global_load_ushort v128, v[88:89], off offset:32
	global_load_ushort v125, v[88:89], off offset:64
	global_load_ushort v126, v[88:89], off offset:96
	global_load_ushort v122, v[86:87], off
	global_load_ushort v123, v[86:87], off offset:32
	global_load_ushort v120, v[86:87], off offset:64
	global_load_ushort v121, v[86:87], off offset:96
	global_load_ushort v118, v[84:85], off
	global_load_ushort v119, v[84:85], off offset:32
	global_load_ushort v116, v[84:85], off offset:64
	global_load_ushort v117, v[84:85], off offset:96
	v_mad_i64_i32 v[92:93], s[0:1], v92, s62, v[108:109]
	s_waitcnt vmcnt(15)
	v_lshlrev_b32_e32 v94, 16, v94
	s_waitcnt vmcnt(14)
	v_lshlrev_b32_e32 v95, 16, v95
	v_pk_add_f32 v[98:99], v[98:99], v[94:95]
	s_waitcnt vmcnt(12)
	v_lshlrev_b32_e32 v95, 16, v115
	v_mov_b32_e32 v115, v60
	global_load_ushort v60, v[110:111], off offset:2048
	global_load_ushort v178, v[110:111], off offset:2080
	global_load_ushort v179, v[110:111], off offset:2112
	global_load_ushort v180, v[110:111], off offset:2144
	v_lshlrev_b32_e32 v94, 16, v114
	v_mov_b32_e32 v114, v78
	v_pk_mul_f32 v[112:113], v[98:99], v[98:99]
	v_pk_add_f32 v[94:95], v[114:115], v[94:95]
	s_waitcnt vmcnt(0)
	v_lshlrev_b32_e32 v60, 16, v60
	v_mul_f32_e32 v70, 0xbfb8aa3b, v60
	v_exp_f32_e32 v70, v70
	v_pk_mul_f32 v[114:115], v[94:95], v[94:95]
	v_add_f32_e32 v70, 1.0, v70
	s_nop 0
	v_rcp_f32_e32 v70, v70
	s_nop 0
	v_mul_f32_e32 v129, v70, v60
	v_lshlrev_b32_e32 v60, 16, v178
	v_mul_f32_e32 v70, 0xbfb8aa3b, v60
	v_exp_f32_e32 v70, v70
	s_nop 0
	v_add_f32_e32 v70, 1.0, v70
	s_nop 0
	v_rcp_f32_e32 v70, v70
	s_nop 0
	v_mul_f32_e32 v78, v70, v60
	v_lshlrev_b32_e32 v60, 16, v179
	v_mul_f32_e32 v70, 0xbfb8aa3b, v60
	v_exp_f32_e32 v70, v70
	s_nop 0
	v_add_f32_e32 v70, 1.0, v70
	s_nop 0
	v_rcp_f32_e32 v70, v70
	s_nop 0
	v_mul_f32_e32 v124, v70, v60
	v_lshlrev_b32_e32 v60, 16, v180
	v_mul_f32_e32 v70, 0xbfb8aa3b, v60
	v_exp_f32_e32 v70, v70
	s_nop 0
	v_add_f32_e32 v70, 1.0, v70
	s_nop 0
	v_rcp_f32_e32 v70, v70
	v_lshlrev_b32_e32 v131, 16, v128
	v_lshlrev_b32_e32 v130, 16, v127
	v_mov_b32_e32 v74, v71
	v_mul_f32_e32 v110, v70, v60
	v_pk_add_f32 v[70:71], v[74:75], v[130:131]
	v_lshlrev_b32_e32 v127, 16, v126
	v_lshlrev_b32_e32 v126, 16, v125
	v_mov_b32_e32 v60, v79
	v_pk_mul_f32 v[74:75], v[70:71], v[70:71]
	v_pk_add_f32 v[60:61], v[60:61], v[126:127]
	v_mov_b32_e32 v130, v74
	v_pk_mul_f32 v[126:127], v[60:61], v[60:61]
	v_mov_b32_e32 v131, v112
	v_mov_b32_e32 v112, v75
	v_pk_add_f32 v[74:75], v[130:131], v[112:113]
	v_mov_b32_e32 v112, v126
	v_mov_b32_e32 v113, v114
	v_pk_add_f32 v[74:75], v[74:75], v[112:113]
	v_mov_b32_e32 v114, v127
	v_pk_add_f32 v[74:75], v[74:75], v[114:115]
	ds_bpermute_b32 v113, v231, v75
	ds_bpermute_b32 v112, v231, v74
	s_waitcnt lgkmcnt(0)
	v_pk_add_f32 v[74:75], v[74:75], v[112:113]
	ds_bpermute_b32 v113, v230, v75
	ds_bpermute_b32 v112, v230, v74
	s_waitcnt lgkmcnt(0)
	v_pk_add_f32 v[74:75], v[74:75], v[112:113]
	ds_bpermute_b32 v113, v229, v75
	ds_bpermute_b32 v112, v229, v74
	s_waitcnt lgkmcnt(0)
	v_pk_add_f32 v[74:75], v[74:75], v[112:113]
	ds_bpermute_b32 v113, v64, v75
	ds_bpermute_b32 v112, v64, v74
	s_waitcnt lgkmcnt(0)
	v_pk_add_f32 v[74:75], v[74:75], v[112:113]
	s_nop 0
	v_pk_fma_f32 v[74:75], v[74:75], s[2:3], v[82:83] op_sel_hi:[1,0,0]
	s_nop 0
	v_mul_f32_e32 v79, 0x4b800000, v75
	v_cmp_gt_f32_e64 s[0:1], s54, v75
	v_cmp_gt_f32_e32 vcc, s54, v74
	s_nop 0
	v_cndmask_b32_e64 v75, v75, v79, s[0:1]
	v_rsq_f32_e32 v75, v75
	s_nop 0
	v_mul_f32_e32 v79, 0x45800000, v75
	v_cndmask_b32_e64 v75, v75, v79, s[0:1]
	v_mul_f32_e32 v79, v98, v75
	global_load_ushort v111, v[100:101], off offset:2048
	global_load_ushort v112, v[100:101], off offset:2080
	global_load_ushort v113, v[100:101], off offset:2112
	global_load_ushort v114, v[100:101], off offset:2144
	global_load_ushort v115, v[96:97], off offset:2048
	global_load_ushort v125, v[96:97], off offset:2080
	s_nop 0
	global_load_ushort v101, v[96:97], off offset:2112
	global_load_ushort v100, v[96:97], off offset:2144
	global_load_ushort v98, v[92:93], off offset:2048
	s_nop 0
	global_load_ushort v97, v[92:93], off offset:2080
	global_load_ushort v96, v[92:93], off offset:2112
	s_nop 0
	global_load_ushort v92, v[92:93], off offset:2144
	v_mul_f32_e32 v79, v209, v79
	v_mul_f32_e32 v79, v129, v79
	v_cvt_pk_bf16_f32 v79, v79, s0
	global_store_short v[90:91], v79, off
	v_mul_f32_e32 v79, v99, v75
	v_mul_f32_e32 v79, v210, v79
	v_mul_f32_e32 v78, v78, v79
	v_cvt_pk_bf16_f32 v78, v78, s0
	global_store_short v[90:91], v78, off offset:32
	v_mul_f32_e32 v78, v94, v75
	v_mul_f32_e32 v75, v95, v75
	v_mul_f32_e32 v75, v212, v75
	v_mul_f32_e32 v75, v110, v75
	v_cvt_pk_bf16_f32 v75, v75, s0
	global_store_short v[90:91], v75, off offset:96
	v_mul_f32_e32 v75, 0x4b800000, v74
	v_cndmask_b32_e32 v74, v74, v75, vcc
	v_rsq_f32_e32 v74, v74
	v_mul_f32_e32 v78, v211, v78
	v_mul_f32_e32 v78, v124, v78
	v_cvt_pk_bf16_f32 v78, v78, s0
	v_mul_f32_e32 v75, 0x45800000, v74
	v_cndmask_b32_e32 v74, v74, v75, vcc
	global_store_short v[90:91], v78, off offset:64
	v_mul_f32_e32 v70, v70, v74
	v_mul_f32_e32 v70, v209, v70
	v_mul_f32_e32 v60, v60, v74
	v_mul_f32_e32 v60, v211, v60
	s_waitcnt vmcnt(15)
; __device__ __forceinline__ bf16_t f2bf(float f) { return (bf16_t)(cvt_pk_bf16(f, 0.f) & 0xffffu); }
; __device__ __forceinline__ float bf2f(bf16_t b) { return __uint_as_float(((unsigned)b) << 16); }
; __device__ __forceinline__ float siluf_(float x) { return x * sigmoidf_(x); }
; template <int MODE>
; __device__ __forceinline__ void hgrn_mfma(const Ctx& C, int l, int z, int b, int hd, int c, f32x4 (&Sacc)[4][4], float& dectot, unsigned char* wl, float lb) {
;     ...
;                 for (int r = 0; r < 4; ++r) { const int st = c * 128 + sc * 32 + 16 * tt + 4 * quad + r; const int tq = z ? 4095 - st : st;
;                     bf16_t* yp = ya + (size_t)(b * SEQ + tq) * 256 + hd * 64 + fr;
;                     float o[4]; float ss = 0.f;
; #pragma unroll
;                     for (int vt = 0; vt < 4; ++vt) { o[vt] = Oacc[tt][vt][r] + bf2f(tmpv[r][vt]); ss += o[vt] * o[vt]; }
;                     ss += __shfl_xor(ss, 1); ss += __shfl_xor(ss, 2); ss += __shfl_xor(ss, 4); ss += __shfl_xor(ss, 8);
;                     const float rs = rsqrtf(ss * (1.f / 64.f) + 1e-6f);
; #pragma unroll
;                     for (int vt = 0; vt < 4; ++vt) yp[16 * vt] = f2bf(o[vt] * rs * gnv[vt] * siluf_(bf2f(gtv[r][vt]))); }
	v_lshlrev_b32_e32 v75, 16, v111
	v_mul_f32_e32 v78, 0xbfb8aa3b, v75
	v_exp_f32_e32 v78, v78
	s_nop 0
	v_add_f32_e32 v78, 1.0, v78
	s_nop 0
	v_rcp_f32_e32 v78, v78
	s_nop 0
	v_mul_f32_e32 v75, v78, v75
	v_mul_f32_e32 v70, v75, v70
	v_cvt_pk_bf16_f32 v70, v70, s0
	global_store_short v[88:89], v70, off
	v_mul_f32_e32 v70, v71, v74
	s_waitcnt vmcnt(15)
	v_lshlrev_b32_e32 v71, 16, v112
	v_mul_f32_e32 v75, 0xbfb8aa3b, v71
	v_exp_f32_e32 v75, v75
	v_mul_f32_e32 v70, v210, v70
	v_add_f32_e32 v75, 1.0, v75
	s_nop 0
	v_rcp_f32_e32 v75, v75
	s_nop 0
	v_mul_f32_e32 v71, v75, v71
	v_mul_f32_e32 v70, v71, v70
	v_cvt_pk_bf16_f32 v70, v70, s0
	global_store_short v[88:89], v70, off offset:32
	s_waitcnt vmcnt(15)
	v_lshlrev_b32_e32 v70, 16, v113
	v_mul_f32_e32 v71, 0xbfb8aa3b, v70
	v_exp_f32_e32 v71, v71
	s_nop 0
	v_add_f32_e32 v71, 1.0, v71
	s_nop 0
	v_rcp_f32_e32 v71, v71
	s_nop 0
	v_mul_f32_e32 v70, v71, v70
	v_mul_f32_e32 v60, v70, v60
	v_cvt_pk_bf16_f32 v60, v60, s0
	global_store_short v[88:89], v60, off offset:64
	v_mul_f32_e32 v60, v61, v74
	s_waitcnt vmcnt(15)
	v_lshlrev_b32_e32 v61, 16, v114
	v_mul_f32_e32 v70, 0xbfb8aa3b, v61
	v_exp_f32_e32 v70, v70
	v_mul_f32_e32 v60, v212, v60
	v_add_f32_e32 v70, 1.0, v70
	s_nop 0
	v_rcp_f32_e32 v70, v70
	v_mov_b32_e32 v75, v62
	s_waitcnt vmcnt(14)
	v_lshlrev_b32_e32 v62, 16, v115
	v_mul_f32_e32 v61, v70, v61
	v_mov_b32_e32 v70, v72
	v_mul_f32_e32 v72, 0xbfb8aa3b, v62
	v_exp_f32_e32 v72, v72
	v_mul_f32_e32 v60, v61, v60
	v_cvt_pk_bf16_f32 v60, v60, s0
	v_mov_b32_e32 v71, v76
	v_add_f32_e32 v72, 1.0, v72
	v_mov_b32_e32 v74, v80
	global_store_short v[88:89], v60, off offset:96
	v_lshlrev_b32_e32 v61, 16, v123
	v_lshlrev_b32_e32 v60, 16, v122
	v_rcp_f32_e32 v72, v72
	s_nop 0
	v_mul_f32_e32 v90, v72, v62
	s_waitcnt vmcnt(14)
	v_lshlrev_b32_e32 v62, 16, v125
	v_mul_f32_e32 v72, 0xbfb8aa3b, v62
	v_exp_f32_e32 v72, v72
	v_pk_add_f32 v[70:71], v[70:71], v[60:61]
	v_lshlrev_b32_e32 v61, 16, v121
	v_lshlrev_b32_e32 v60, 16, v120
	v_add_f32_e32 v72, 1.0, v72
	v_pk_mul_f32 v[78:79], v[70:71], v[70:71]
	v_pk_add_f32 v[60:61], v[74:75], v[60:61]
	v_rcp_f32_e32 v72, v72
	s_nop 0
	v_mul_f32_e32 v91, v72, v62
	s_waitcnt vmcnt(13)
	v_lshlrev_b32_e32 v62, 16, v101
	v_mul_f32_e32 v72, 0xbfb8aa3b, v62
	v_exp_f32_e32 v72, v72
	v_pk_mul_f32 v[74:75], v[60:61], v[60:61]
	v_add_f32_e32 v72, 1.0, v72
	s_nop 0
	v_rcp_f32_e32 v72, v72
	s_nop 0
	v_mul_f32_e32 v93, v72, v62
	s_waitcnt vmcnt(12)
	v_lshlrev_b32_e32 v62, 16, v100
	v_mul_f32_e32 v72, 0xbfb8aa3b, v62
	v_exp_f32_e32 v72, v72
	s_nop 0
	v_add_f32_e32 v72, 1.0, v72
	s_nop 0
	v_rcp_f32_e32 v72, v72
	v_lshlrev_b32_e32 v89, 16, v119
	v_lshlrev_b32_e32 v88, 16, v118
	v_mov_b32_e32 v76, v73
	v_mul_f32_e32 v94, v72, v62
	v_pk_add_f32 v[72:73], v[76:77], v[88:89]
	v_lshlrev_b32_e32 v89, 16, v117
	v_lshlrev_b32_e32 v88, 16, v116
	v_mov_b32_e32 v62, v81
	v_pk_mul_f32 v[76:77], v[72:73], v[72:73]
	v_pk_add_f32 v[62:63], v[62:63], v[88:89]
	v_mov_b32_e32 v88, v76
	v_pk_mul_f32 v[80:81], v[62:63], v[62:63]
	v_mov_b32_e32 v89, v78
	v_mov_b32_e32 v78, v77
	v_pk_add_f32 v[76:77], v[88:89], v[78:79]
	v_mov_b32_e32 v78, v80
	v_mov_b32_e32 v79, v74
	v_pk_add_f32 v[76:77], v[76:77], v[78:79]
	v_mov_b32_e32 v74, v81
	v_pk_add_f32 v[74:75], v[76:77], v[74:75]
	ds_bpermute_b32 v77, v231, v75
	ds_bpermute_b32 v76, v231, v74
	s_waitcnt lgkmcnt(0)
	v_pk_add_f32 v[74:75], v[74:75], v[76:77]
	ds_bpermute_b32 v77, v230, v75
	ds_bpermute_b32 v76, v230, v74
	s_waitcnt lgkmcnt(0)
	v_pk_add_f32 v[74:75], v[74:75], v[76:77]
	ds_bpermute_b32 v77, v229, v75
	ds_bpermute_b32 v76, v229, v74
	s_waitcnt lgkmcnt(0)
	v_pk_add_f32 v[74:75], v[74:75], v[76:77]
	ds_bpermute_b32 v77, v64, v75
	ds_bpermute_b32 v76, v64, v74
	s_waitcnt lgkmcnt(0)
	v_pk_add_f32 v[74:75], v[74:75], v[76:77]
	s_nop 0
	v_pk_fma_f32 v[74:75], v[74:75], s[2:3], v[82:83] op_sel_hi:[1,0,0]
	s_nop 0
	v_mul_f32_e32 v64, 0x4b800000, v75
	v_cmp_gt_f32_e64 s[0:1], s54, v75
	v_cmp_gt_f32_e32 vcc, s54, v74
	s_nop 0
	v_cndmask_b32_e64 v64, v75, v64, s[0:1]
	v_rsq_f32_e32 v64, v64
	s_nop 0
	v_mul_f32_e32 v75, 0x45800000, v64
	v_cndmask_b32_e64 v64, v64, v75, s[0:1]
	v_mul_f32_e32 v60, v60, v64
	v_mul_f32_e32 v70, v70, v64
	v_mul_f32_e32 v60, v211, v60
	v_mul_f32_e32 v70, v209, v70
	v_mul_f32_e32 v60, v93, v60
	v_mul_f32_e32 v70, v90, v70
	v_cvt_pk_bf16_f32 v60, v60, s0
	v_cvt_pk_bf16_f32 v70, v70, s0
	global_store_short v[86:87], v60, off offset:64
	v_mul_f32_e32 v60, v61, v64
	global_store_short v[86:87], v70, off
	v_mul_f32_e32 v70, v71, v64
	v_mul_f32_e32 v60, v212, v60
	v_mul_f32_e32 v70, v210, v70
	v_mul_f32_e32 v60, v94, v60
	v_mul_f32_e32 v70, v91, v70
	v_cvt_pk_bf16_f32 v60, v60, s0
	v_cvt_pk_bf16_f32 v70, v70, s0
	global_store_short v[86:87], v60, off offset:96
	v_mul_f32_e32 v60, 0x4b800000, v74
	s_waitcnt vmcnt(14)
	v_lshlrev_b32_e32 v64, 16, v98
	global_store_short v[86:87], v70, off offset:32
	v_cndmask_b32_e32 v60, v74, v60, vcc
	v_mul_f32_e32 v70, 0xbfb8aa3b, v64
	v_rsq_f32_e32 v60, v60
	v_exp_f32_e32 v70, v70
	v_mul_f32_e32 v61, 0x45800000, v60
	v_add_f32_e32 v70, 1.0, v70
	v_cndmask_b32_e32 v60, v60, v61, vcc
	v_mul_f32_e32 v61, v72, v60
	v_mul_f32_e32 v61, v209, v61
	v_rcp_f32_e32 v70, v70
	s_nop 0
	v_mul_f32_e32 v64, v70, v64
	v_mul_f32_e32 v61, v64, v61
	s_waitcnt vmcnt(14)
	v_lshlrev_b32_e32 v64, 16, v97
	v_mul_f32_e32 v70, 0xbfb8aa3b, v64
	v_exp_f32_e32 v70, v70
	v_cvt_pk_bf16_f32 v61, v61, s0
	global_store_short v[84:85], v61, off
	v_mul_f32_e32 v61, v73, v60
	v_add_f32_e32 v70, 1.0, v70
	v_mul_f32_e32 v61, v210, v61
	v_rcp_f32_e32 v70, v70
	s_nop 0
	v_mul_f32_e32 v64, v70, v64
	v_mul_f32_e32 v61, v64, v61
	v_cvt_pk_bf16_f32 v61, v61, s0
	global_store_short v[84:85], v61, off offset:32
	v_mul_f32_e32 v61, v62, v60
	s_waitcnt vmcnt(15)
	v_lshlrev_b32_e32 v62, 16, v96
	v_mul_f32_e32 v64, 0xbfb8aa3b, v62
	v_exp_f32_e32 v64, v64
	v_mul_f32_e32 v61, v211, v61
	v_mul_f32_e32 v60, v63, v60
	v_mul_f32_e32 v60, v212, v60
	v_add_f32_e32 v64, 1.0, v64
	s_nop 0
	v_rcp_f32_e32 v64, v64
	s_nop 0
	v_mul_f32_e32 v62, v64, v62
	v_mul_f32_e32 v61, v62, v61
	v_cvt_pk_bf16_f32 v61, v61, s0
	global_store_short v[84:85], v61, off offset:64
	s_waitcnt vmcnt(15)
	v_lshlrev_b32_e32 v61, 16, v92
	v_mul_f32_e32 v62, 0xbfb8aa3b, v61
	v_exp_f32_e32 v62, v62
	s_nop 0
	v_add_f32_e32 v62, 1.0, v62
	s_nop 0
	v_rcp_f32_e32 v62, v62
	s_nop 0
	v_mul_f32_e32 v61, v62, v61
	v_mul_f32_e32 v60, v61, v60
	v_cvt_pk_bf16_f32 v60, v60, s0
	global_store_short v[84:85], v60, off offset:96
	s_waitcnt lgkmcnt(0)
	s_cbranch_scc0 .LBB0_742
	v_readlane_b32 s0, v254, 20
	s_add_i32 s73, s73, s0
	s_cmpk_gt_i32 s73, 0x3ff
	v_readlane_b32 s1, v254, 21
	s_cbranch_scc0 .LBB0_739
;     __device__ __forceinline__ bf16_t* bfp(size_t off) const { return (bf16_t*)(ws + off); }
; __device__ __forceinline__ void hy_out_tr_item(const Ctx& C, int item) {
;     const int cb = item / 512, tb = item % 512, lane = C.lane, tok0 = tb * 64;
;     bf16_t* tile = (bf16_t*)(C.lds + C.wave * 8704);
;     const bf16_t* yct = C.bfp(OFF_YCT); bf16_t* yc = C.bfp(OFF_YC);
; #pragma unroll 1
;     for (int c0 = 0; c0 < 64; c0 += 16) { bf16_t tv_[16];
; #pragma unroll
;         for (int q = 0; q < 16; ++q) tv_[q] = yct[(size_t)(cb * 64 + c0 + q) * M_TOK + tok0 + lane];
; __global__ void __launch_bounds__(NTHR, 2) fwd_megakernel(Params prm) {
;     ...
;         __syncthreads();
;         for (int _m = 0; _m < REP_MIXC; ++_m) { for (int it = bid * 8 + C.wave; it < 2048; it += G * 8) hy_out_tr_item(C, it);
.LBB0_746:
	v_readlane_b32 s14, v253, 32
	s_add_i32 s68, s69, s14
	s_cmpk_lt_i32 s68, 0x800
	s_mov_b32 s14, 0x100000
	s_mov_b64 s[12:13], 0x100000
	v_mov_b32_e32 v238, 0x358637bd
	s_barrier
	s_cbranch_scc0 .LBB0_751
	s_mulk_i32 s69, 0x2200
	s_add_i32 s4, s69, 0
	v_lshlrev_b32_e32 v64, 1, v132
	v_lshl_add_u64 v[0:1], s[38:39], 0, v[64:65]
	s_mov_b64 s[0:1], 0x6000000
	v_mov_b32_e32 v2, s4
	v_lshl_add_u64 v[0:1], v[0:1], 0, s[0:1]
	v_mad_u32_u24 v14, v132, s3, v2
	s_movk_i32 s0, 0xff7e
	v_mad_i32_i24 v15, v132, s0, v14
	v_readlane_b32 s0, v254, 30
	s_add_u32 s0, s0, s30
	v_readlane_b32 s1, v254, 31
	s_addc_u32 s1, s1, s31
	s_nop 0
	v_lshl_add_u64 v[2:3], s[0:1], 0, v[64:65]

; __device__ __forceinline__ unsigned cvt_pk_bf16(float lo, float hi) { f32x2_t v = {lo, hi}; bf2_t r = __builtin_convertvector(v, bf2_t); return __builtin_bit_cast(unsigned, r); }
; __device__ __forceinline__ float bflo(unsigned u) { return __uint_as_float(u << 16); }
; __device__ __forceinline__ float bfhi(unsigned u) { return __uint_as_float(u & 0xffff0000u); }
;     __device__ __forceinline__ bf16_t* bfp(size_t off) const { return (bf16_t*)(ws + off); }
;     __device__ __forceinline__ float* fp(size_t off) const { return (float*)(ws + off); }
; __device__ __forceinline__ void attn_combine(const Ctx& C) {
;     const bf16_t* pd = C.bfp(OFF_PROJD); const float* lse = C.fp(OFF_LSE); bf16_t* yd = C.bfp(OFF_YD);
;     for (int idx = C.bid * NTHR + C.tid; idx < M_TOK * 32; idx += C.G * NTHR) {
;         const int tok = idx >> 5, j = (idx >> 3) & 3, c8 = idx & 7;
;         const float l0 = lse[((size_t)0 * M_TOK + tok) * 4 + j], l1 = lse[((size_t)1 * M_TOK + tok) * 4 + j], l2 = lse[((size_t)2 * M_TOK + tok) * 4 + j];
;         const float mx = fmaxf(l0, fmaxf(l1, l2)); float w0 = __expf(l0 - mx), w1 = __expf(l1 - mx), w2 = __expf(l2 - mx); const float inv = 1.0f / (w0 + w1 + w2); w0 *= inv; w1 *= inv; w2 *= inv;
;         const bf16_t* row = pd + (size_t)tok * 2304 + j * 64 + c8 * 8;
;         const u32x4 o0 = *(const u32x4*)row, o1 = *(const u32x4*)(row + 256), o2 = *(const u32x4*)(row + 512);
;         u32x4 o;
;         o.x = cvt_pk_bf16(w0 * bflo(o0.x) + w1 * bflo(o1.x) + w2 * bflo(o2.x), w0 * bfhi(o0.x) + w1 * bfhi(o1.x) + w2 * bfhi(o2.x));
;         o.y = cvt_pk_bf16(w0 * bflo(o0.y) + w1 * bflo(o1.y) + w2 * bflo(o2.y), w0 * bfhi(o0.y) + w1 * bfhi(o1.y) + w2 * bfhi(o2.y));
;         o.z = cvt_pk_bf16(w0 * bflo(o0.z) + w1 * bflo(o1.z) + w2 * bflo(o2.z), w0 * bfhi(o0.z) + w1 * bfhi(o1.z) + w2 * bfhi(o2.z));
;         o.w = cvt_pk_bf16(w0 * bflo(o0.w) + w1 * bflo(o1.w) + w2 * bflo(o2.w), w0 * bfhi(o0.w) + w1 * bfhi(o1.w) + w2 * bfhi(o2.w));
;         *(u32x4*)(yd + (size_t)tok * 256 + j * 64 + c8 * 8) = o;
.LBB0_751:
	s_cmpk_lg_i32 s26, 0x100
	s_cbranch_scc1 .Lmy_cmb_generic
	v_readlane_b32 s100, v253, 25
	s_mov_b32 s101, 0
.Lmy_cmb_pass:
	s_add_u32 s4, s24, 0xe000000
	s_addc_u32 s5, s25, 0
	s_add_u32 s6, s24, 0x1a000000
	s_addc_u32 s7, s25, 0
	s_add_u32 s8, s24, 0x1b180000
	s_addc_u32 s9, s25, 0
	v_add_u32_e32 v0, s100, v224
	v_lshrrev_b32_e32 v1, 5, v0
	v_bfe_u32 v2, v0, 3, 2
	v_and_b32_e32 v3, 7, v0
	v_lshlrev_b32_e32 v4, 7, v2
	v_lshl_add_u32 v4, v3, 4, v4
	v_lshlrev_b32_e32 v5, 2, v2
	v_lshl_add_u32 v10, v1, 4, v5
	v_add_u32_e32 v11, 0x80000, v10
	v_add_u32_e32 v12, 0x100000, v10
	s_movk_i32 s0, 0x1200
	v_mad_u32_u24 v13, v1, s0, v4
	v_lshl_add_u32 v14, v1, 9, v4
	global_load_dword v164, v10, s[6:7]
	global_load_dword v165, v11, s[6:7]
	global_load_dword v166, v12, s[6:7]
	s_add_u32 s6, s6, 0x10000
	s_addc_u32 s7, s7, 0
	global_load_dword v167, v10, s[6:7]
	global_load_dword v168, v11, s[6:7]
	global_load_dword v169, v12, s[6:7]
	s_add_u32 s6, s6, 0x10000
	s_addc_u32 s7, s7, 0
	global_load_dword v170, v10, s[6:7]
	global_load_dword v171, v11, s[6:7]
	global_load_dword v172, v12, s[6:7]
	s_add_u32 s6, s6, 0x10000
	s_addc_u32 s7, s7, 0
	global_load_dword v173, v10, s[6:7]
	global_load_dword v174, v11, s[6:7]
	global_load_dword v175, v12, s[6:7]
	s_add_u32 s6, s6, 0x10000
	s_addc_u32 s7, s7, 0
	global_load_dword v176, v10, s[6:7]
	global_load_dword v177, v11, s[6:7]
	global_load_dword v178, v12, s[6:7]
	s_add_u32 s6, s6, 0x10000
	s_addc_u32 s7, s7, 0
	global_load_dword v179, v10, s[6:7]
	global_load_dword v180, v11, s[6:7]
	global_load_dword v181, v12, s[6:7]
	s_add_u32 s6, s6, 0x10000
	s_addc_u32 s7, s7, 0
	global_load_dword v188, v10, s[6:7]
	global_load_dword v189, v11, s[6:7]
	global_load_dword v190, v12, s[6:7]
	s_add_u32 s6, s6, 0x10000
	s_addc_u32 s7, s7, 0
	global_load_dword v191, v10, s[6:7]
	global_load_dword v192, v11, s[6:7]
	global_load_dword v193, v12, s[6:7]
	global_load_dwordx4 v[68:71], v13, s[4:5]
	global_load_dwordx4 v[72:75], v13, s[4:5] offset:512
	global_load_dwordx4 v[76:79], v13, s[4:5] offset:1024
	s_add_u32 s4, s4, 0x1200000
	s_addc_u32 s5, s5, 0
	global_load_dwordx4 v[80:83], v13, s[4:5]
	global_load_dwordx4 v[84:87], v13, s[4:5] offset:512
	global_load_dwordx4 v[88:91], v13, s[4:5] offset:1024
	s_add_u32 s4, s4, 0x1200000
	s_addc_u32 s5, s5, 0
	global_load_dwordx4 v[92:95], v13, s[4:5]
	global_load_dwordx4 v[96:99], v13, s[4:5] offset:512
	global_load_dwordx4 v[100:103], v13, s[4:5] offset:1024
	s_add_u32 s4, s4, 0x1200000
	s_addc_u32 s5, s5, 0
	global_load_dwordx4 v[104:107], v13, s[4:5]
	global_load_dwordx4 v[108:111], v13, s[4:5] offset:512
	global_load_dwordx4 v[112:115], v13, s[4:5] offset:1024
	s_add_u32 s4, s4, 0x1200000
	s_addc_u32 s5, s5, 0
	global_load_dwordx4 v[116:119], v13, s[4:5]
	global_load_dwordx4 v[120:123], v13, s[4:5] offset:512
	global_load_dwordx4 v[124:127], v13, s[4:5] offset:1024
	s_add_u32 s4, s4, 0x1200000
	s_addc_u32 s5, s5, 0
	global_load_dwordx4 v[128:131], v13, s[4:5]
	global_load_dwordx4 v[132:135], v13, s[4:5] offset:512
	global_load_dwordx4 v[136:139], v13, s[4:5] offset:1024
	s_add_u32 s4, s4, 0x1200000
	s_addc_u32 s5, s5, 0
	global_load_dwordx4 v[140:143], v13, s[4:5]
	global_load_dwordx4 v[144:147], v13, s[4:5] offset:512
	global_load_dwordx4 v[148:151], v13, s[4:5] offset:1024
	s_add_u32 s4, s4, 0x1200000
	s_addc_u32 s5, s5, 0
	global_load_dwordx4 v[152:155], v13, s[4:5]
	global_load_dwordx4 v[156:159], v13, s[4:5] offset:512
	global_load_dwordx4 v[160:163], v13, s[4:5] offset:1024
	s_waitcnt vmcnt(45)
	v_max3_f32 v20, v164, v165, v166
	v_sub_f32_e32 v21, v164, v20
	v_sub_f32_e32 v22, v165, v20
	v_sub_f32_e32 v23, v166, v20
	v_mul_f32_e32 v21, 0x3fb8aa3b, v21
	v_mul_f32_e32 v22, 0x3fb8aa3b, v22
	v_mul_f32_e32 v23, 0x3fb8aa3b, v23
	v_exp_f32_e32 v21, v21
	v_exp_f32_e32 v22, v22
	v_exp_f32_e32 v23, v23
	s_nop 0
	v_add_f32_e32 v24, v21, v22
	v_add_f32_e32 v24, v23, v24
	v_rcp_f32_e32 v24, v24
	s_nop 0
	v_mul_f32_e32 v21, v21, v24
	v_mul_f32_e32 v22, v22, v24
	v_mul_f32_e32 v23, v23, v24
	s_waitcnt vmcnt(21)
	v_lshlrev_b32_e32 v25, 16, v68
	v_and_b32_e32 v26, 0xffff0000, v68
	v_lshlrev_b32_e32 v27, 16, v72
	v_and_b32_e32 v28, 0xffff0000, v72
	v_lshlrev_b32_e32 v29, 16, v76
	v_and_b32_e32 v30, 0xffff0000, v76
	v_mul_f32_e32 v31, v21, v25
	v_mul_f32_e32 v32, v22, v28
	v_fmac_f32_e32 v31, v22, v27
	v_fmac_f32_e32 v32, v21, v26
	v_fmac_f32_e32 v31, v23, v29
	v_fmac_f32_e32 v32, v23, v30
	v_cvt_pk_bf16_f32 v68, v31, v32
	v_lshlrev_b32_e32 v25, 16, v69
	v_and_b32_e32 v26, 0xffff0000, v69
	v_lshlrev_b32_e32 v27, 16, v73
	v_and_b32_e32 v28, 0xffff0000, v73
	v_lshlrev_b32_e32 v29, 16, v77
	v_and_b32_e32 v30, 0xffff0000, v77
	v_mul_f32_e32 v31, v21, v25
	v_mul_f32_e32 v32, v22, v28
	v_fmac_f32_e32 v31, v22, v27
	v_fmac_f32_e32 v32, v21, v26
	v_fmac_f32_e32 v31, v23, v29
	v_fmac_f32_e32 v32, v23, v30
	v_cvt_pk_bf16_f32 v69, v31, v32
	v_lshlrev_b32_e32 v25, 16, v70
	v_and_b32_e32 v26, 0xffff0000, v70
	v_lshlrev_b32_e32 v27, 16, v74
	v_and_b32_e32 v28, 0xffff0000, v74
	v_lshlrev_b32_e32 v29, 16, v78
	v_and_b32_e32 v30, 0xffff0000, v78
	v_mul_f32_e32 v31, v21, v25
	v_mul_f32_e32 v32, v22, v28
	v_fmac_f32_e32 v31, v22, v27
	v_fmac_f32_e32 v32, v21, v26
	v_fmac_f32_e32 v31, v23, v29
	v_fmac_f32_e32 v32, v23, v30
	v_cvt_pk_bf16_f32 v70, v31, v32
	v_lshlrev_b32_e32 v25, 16, v71
	v_and_b32_e32 v26, 0xffff0000, v71
	v_lshlrev_b32_e32 v27, 16, v75
	v_and_b32_e32 v28, 0xffff0000, v75
	v_lshlrev_b32_e32 v29, 16, v79
	v_and_b32_e32 v30, 0xffff0000, v79
	v_mul_f32_e32 v31, v21, v25
	v_mul_f32_e32 v32, v22, v28
	v_fmac_f32_e32 v31, v22, v27
	v_fmac_f32_e32 v32, v21, v26
	v_fmac_f32_e32 v31, v23, v29
	v_fmac_f32_e32 v32, v23, v30
	v_cvt_pk_bf16_f32 v71, v31, v32
	global_store_dwordx4 v14, v[68:71], s[8:9]
	s_add_u32 s8, s8, 0x200000
	s_addc_u32 s9, s9, 0
	v_max3_f32 v20, v167, v168, v169
	v_sub_f32_e32 v21, v167, v20
	v_sub_f32_e32 v22, v168, v20
	v_sub_f32_e32 v23, v169, v20
	v_mul_f32_e32 v21, 0x3fb8aa3b, v21
	v_mul_f32_e32 v22, 0x3fb8aa3b, v22
	v_mul_f32_e32 v23, 0x3fb8aa3b, v23
	v_exp_f32_e32 v21, v21
	v_exp_f32_e32 v22, v22
	v_exp_f32_e32 v23, v23
	s_nop 0
	v_add_f32_e32 v24, v21, v22
	v_add_f32_e32 v24, v23, v24
	v_rcp_f32_e32 v24, v24
	s_nop 0
	v_mul_f32_e32 v21, v21, v24
	v_mul_f32_e32 v22, v22, v24
	v_mul_f32_e32 v23, v23, v24
	s_waitcnt vmcnt(19)
; __device__ __forceinline__ unsigned cvt_pk_bf16(float lo, float hi) { f32x2_t v = {lo, hi}; bf2_t r = __builtin_convertvector(v, bf2_t); return __builtin_bit_cast(unsigned, r); }
; __device__ __forceinline__ float bflo(unsigned u) { return __uint_as_float(u << 16); }
; __device__ __forceinline__ float bfhi(unsigned u) { return __uint_as_float(u & 0xffff0000u); }
; __device__ __forceinline__ void attn_combine(const Ctx& C) {
;     ...
;         const int tok = idx >> 5, j = (idx >> 3) & 3, c8 = idx & 7;
;         const float l0 = lse[((size_t)0 * M_TOK + tok) * 4 + j], l1 = lse[((size_t)1 * M_TOK + tok) * 4 + j], l2 = lse[((size_t)2 * M_TOK + tok) * 4 + j];
;         const float mx = fmaxf(l0, fmaxf(l1, l2)); float w0 = __expf(l0 - mx), w1 = __expf(l1 - mx), w2 = __expf(l2 - mx); const float inv = 1.0f / (w0 + w1 + w2); w0 *= inv; w1 *= inv; w2 *= inv;
;         const bf16_t* row = pd + (size_t)tok * 2304 + j * 64 + c8 * 8;
;         const u32x4 o0 = *(const u32x4*)row, o1 = *(const u32x4*)(row + 256), o2 = *(const u32x4*)(row + 512);
;         u32x4 o;
;         o.x = cvt_pk_bf16(w0 * bflo(o0.x) + w1 * bflo(o1.x) + w2 * bflo(o2.x), w0 * bfhi(o0.x) + w1 * bfhi(o1.x) + w2 * bfhi(o2.x));
;         o.y = cvt_pk_bf16(w0 * bflo(o0.y) + w1 * bflo(o1.y) + w2 * bflo(o2.y), w0 * bfhi(o0.y) + w1 * bfhi(o1.y) + w2 * bfhi(o2.y));
;         o.z = cvt_pk_bf16(w0 * bflo(o0.z) + w1 * bflo(o1.z) + w2 * bflo(o2.z), w0 * bfhi(o0.z) + w1 * bfhi(o1.z) + w2 * bfhi(o2.z));
;         o.w = cvt_pk_bf16(w0 * bflo(o0.w) + w1 * bflo(o1.w) + w2 * bflo(o2.w), w0 * bfhi(o0.w) + w1 * bfhi(o1.w) + w2 * bfhi(o2.w));
;         *(u32x4*)(yd + (size_t)tok * 256 + j * 64 + c8 * 8) = o;
	v_lshlrev_b32_e32 v25, 16, v80
	v_and_b32_e32 v26, 0xffff0000, v80
	v_lshlrev_b32_e32 v27, 16, v84
	v_and_b32_e32 v28, 0xffff0000, v84
	v_lshlrev_b32_e32 v29, 16, v88
	v_and_b32_e32 v30, 0xffff0000, v88
	v_mul_f32_e32 v31, v21, v25
	v_mul_f32_e32 v32, v22, v28
	v_fmac_f32_e32 v31, v22, v27
	v_fmac_f32_e32 v32, v21, v26
	v_fmac_f32_e32 v31, v23, v29
	v_fmac_f32_e32 v32, v23, v30
	v_cvt_pk_bf16_f32 v80, v31, v32
	v_lshlrev_b32_e32 v25, 16, v81
	v_and_b32_e32 v26, 0xffff0000, v81
	v_lshlrev_b32_e32 v27, 16, v85
	v_and_b32_e32 v28, 0xffff0000, v85
	v_lshlrev_b32_e32 v29, 16, v89
	v_and_b32_e32 v30, 0xffff0000, v89
	v_mul_f32_e32 v31, v21, v25
	v_mul_f32_e32 v32, v22, v28
	v_fmac_f32_e32 v31, v22, v27
	v_fmac_f32_e32 v32, v21, v26
	v_fmac_f32_e32 v31, v23, v29
	v_fmac_f32_e32 v32, v23, v30
	v_cvt_pk_bf16_f32 v81, v31, v32
	v_lshlrev_b32_e32 v25, 16, v82
	v_and_b32_e32 v26, 0xffff0000, v82
	v_lshlrev_b32_e32 v27, 16, v86
	v_and_b32_e32 v28, 0xffff0000, v86
	v_lshlrev_b32_e32 v29, 16, v90
	v_and_b32_e32 v30, 0xffff0000, v90
	v_mul_f32_e32 v31, v21, v25
	v_mul_f32_e32 v32, v22, v28
	v_fmac_f32_e32 v31, v22, v27
	v_fmac_f32_e32 v32, v21, v26
	v_fmac_f32_e32 v31, v23, v29
	v_fmac_f32_e32 v32, v23, v30
	v_cvt_pk_bf16_f32 v82, v31, v32
	v_lshlrev_b32_e32 v25, 16, v83
	v_and_b32_e32 v26, 0xffff0000, v83
	v_lshlrev_b32_e32 v27, 16, v87
	v_and_b32_e32 v28, 0xffff0000, v87
	v_lshlrev_b32_e32 v29, 16, v91
	v_and_b32_e32 v30, 0xffff0000, v91
	v_mul_f32_e32 v31, v21, v25
	v_mul_f32_e32 v32, v22, v28
	v_fmac_f32_e32 v31, v22, v27
	v_fmac_f32_e32 v32, v21, v26
	v_fmac_f32_e32 v31, v23, v29
	v_fmac_f32_e32 v32, v23, v30
	v_cvt_pk_bf16_f32 v83, v31, v32
	global_store_dwordx4 v14, v[80:83], s[8:9]
	s_add_u32 s8, s8, 0x200000
	s_addc_u32 s9, s9, 0
	v_max3_f32 v20, v170, v171, v172
	v_sub_f32_e32 v21, v170, v20
	v_sub_f32_e32 v22, v171, v20
	v_sub_f32_e32 v23, v172, v20
	v_mul_f32_e32 v21, 0x3fb8aa3b, v21
	v_mul_f32_e32 v22, 0x3fb8aa3b, v22
	v_mul_f32_e32 v23, 0x3fb8aa3b, v23
	v_exp_f32_e32 v21, v21
	v_exp_f32_e32 v22, v22
	v_exp_f32_e32 v23, v23
	s_nop 0
	v_add_f32_e32 v24, v21, v22
	v_add_f32_e32 v24, v23, v24
	v_rcp_f32_e32 v24, v24
	s_nop 0
	v_mul_f32_e32 v21, v21, v24
	v_mul_f32_e32 v22, v22, v24
	v_mul_f32_e32 v23, v23, v24
	s_waitcnt vmcnt(17)
	v_lshlrev_b32_e32 v25, 16, v92
	v_and_b32_e32 v26, 0xffff0000, v92
	v_lshlrev_b32_e32 v27, 16, v96
	v_and_b32_e32 v28, 0xffff0000, v96
	v_lshlrev_b32_e32 v29, 16, v100
	v_and_b32_e32 v30, 0xffff0000, v100
	v_mul_f32_e32 v31, v21, v25
	v_mul_f32_e32 v32, v22, v28
	v_fmac_f32_e32 v31, v22, v27
	v_fmac_f32_e32 v32, v21, v26
	v_fmac_f32_e32 v31, v23, v29
	v_fmac_f32_e32 v32, v23, v30
	v_cvt_pk_bf16_f32 v92, v31, v32
	v_lshlrev_b32_e32 v25, 16, v93
	v_and_b32_e32 v26, 0xffff0000, v93
	v_lshlrev_b32_e32 v27, 16, v97
	v_and_b32_e32 v28, 0xffff0000, v97
	v_lshlrev_b32_e32 v29, 16, v101
	v_and_b32_e32 v30, 0xffff0000, v101
	v_mul_f32_e32 v31, v21, v25
	v_mul_f32_e32 v32, v22, v28
	v_fmac_f32_e32 v31, v22, v27
	v_fmac_f32_e32 v32, v21, v26
	v_fmac_f32_e32 v31, v23, v29
	v_fmac_f32_e32 v32, v23, v30
	v_cvt_pk_bf16_f32 v93, v31, v32
	v_lshlrev_b32_e32 v25, 16, v94
	v_and_b32_e32 v26, 0xffff0000, v94
	v_lshlrev_b32_e32 v27, 16, v98
	v_and_b32_e32 v28, 0xffff0000, v98
	v_lshlrev_b32_e32 v29, 16, v102
	v_and_b32_e32 v30, 0xffff0000, v102
	v_mul_f32_e32 v31, v21, v25
	v_mul_f32_e32 v32, v22, v28
	v_fmac_f32_e32 v31, v22, v27
	v_fmac_f32_e32 v32, v21, v26
	v_fmac_f32_e32 v31, v23, v29
	v_fmac_f32_e32 v32, v23, v30
	v_cvt_pk_bf16_f32 v94, v31, v32
	v_lshlrev_b32_e32 v25, 16, v95
	v_and_b32_e32 v26, 0xffff0000, v95
	v_lshlrev_b32_e32 v27, 16, v99
	v_and_b32_e32 v28, 0xffff0000, v99
	v_lshlrev_b32_e32 v29, 16, v103
	v_and_b32_e32 v30, 0xffff0000, v103
	v_mul_f32_e32 v31, v21, v25
	v_mul_f32_e32 v32, v22, v28
	v_fmac_f32_e32 v31, v22, v27
	v_fmac_f32_e32 v32, v21, v26
	v_fmac_f32_e32 v31, v23, v29
	v_fmac_f32_e32 v32, v23, v30
	v_cvt_pk_bf16_f32 v95, v31, v32
	global_store_dwordx4 v14, v[92:95], s[8:9]
	s_add_u32 s8, s8, 0x200000
	s_addc_u32 s9, s9, 0
	v_max3_f32 v20, v173, v174, v175
	v_sub_f32_e32 v21, v173, v20
	v_sub_f32_e32 v22, v174, v20
	v_sub_f32_e32 v23, v175, v20
	v_mul_f32_e32 v21, 0x3fb8aa3b, v21
	v_mul_f32_e32 v22, 0x3fb8aa3b, v22
	v_mul_f32_e32 v23, 0x3fb8aa3b, v23
	v_exp_f32_e32 v21, v21
	v_exp_f32_e32 v22, v22
	v_exp_f32_e32 v23, v23
	s_nop 0
	v_add_f32_e32 v24, v21, v22
	v_add_f32_e32 v24, v23, v24
	v_rcp_f32_e32 v24, v24
	s_nop 0
	v_mul_f32_e32 v21, v21, v24
	v_mul_f32_e32 v22, v22, v24
	v_mul_f32_e32 v23, v23, v24
	s_waitcnt vmcnt(15)
; __device__ __forceinline__ unsigned cvt_pk_bf16(float lo, float hi) { f32x2_t v = {lo, hi}; bf2_t r = __builtin_convertvector(v, bf2_t); return __builtin_bit_cast(unsigned, r); }
; __device__ __forceinline__ float bflo(unsigned u) { return __uint_as_float(u << 16); }
; __device__ __forceinline__ float bfhi(unsigned u) { return __uint_as_float(u & 0xffff0000u); }
; __device__ __forceinline__ void attn_combine(const Ctx& C) {
;     ...
;         const int tok = idx >> 5, j = (idx >> 3) & 3, c8 = idx & 7;
;         const float l0 = lse[((size_t)0 * M_TOK + tok) * 4 + j], l1 = lse[((size_t)1 * M_TOK + tok) * 4 + j], l2 = lse[((size_t)2 * M_TOK + tok) * 4 + j];
;         const float mx = fmaxf(l0, fmaxf(l1, l2)); float w0 = __expf(l0 - mx), w1 = __expf(l1 - mx), w2 = __expf(l2 - mx); const float inv = 1.0f / (w0 + w1 + w2); w0 *= inv; w1 *= inv; w2 *= inv;
;         const bf16_t* row = pd + (size_t)tok * 2304 + j * 64 + c8 * 8;
;         const u32x4 o0 = *(const u32x4*)row, o1 = *(const u32x4*)(row + 256), o2 = *(const u32x4*)(row + 512);
;         u32x4 o;
;         o.x = cvt_pk_bf16(w0 * bflo(o0.x) + w1 * bflo(o1.x) + w2 * bflo(o2.x), w0 * bfhi(o0.x) + w1 * bfhi(o1.x) + w2 * bfhi(o2.x));
;         o.y = cvt_pk_bf16(w0 * bflo(o0.y) + w1 * bflo(o1.y) + w2 * bflo(o2.y), w0 * bfhi(o0.y) + w1 * bfhi(o1.y) + w2 * bfhi(o2.y));
;         o.z = cvt_pk_bf16(w0 * bflo(o0.z) + w1 * bflo(o1.z) + w2 * bflo(o2.z), w0 * bfhi(o0.z) + w1 * bfhi(o1.z) + w2 * bfhi(o2.z));
;         o.w = cvt_pk_bf16(w0 * bflo(o0.w) + w1 * bflo(o1.w) + w2 * bflo(o2.w), w0 * bfhi(o0.w) + w1 * bfhi(o1.w) + w2 * bfhi(o2.w));
;         *(u32x4*)(yd + (size_t)tok * 256 + j * 64 + c8 * 8) = o;
	v_lshlrev_b32_e32 v25, 16, v104
	v_and_b32_e32 v26, 0xffff0000, v104
	v_lshlrev_b32_e32 v27, 16, v108
	v_and_b32_e32 v28, 0xffff0000, v108
	v_lshlrev_b32_e32 v29, 16, v112
	v_and_b32_e32 v30, 0xffff0000, v112
	v_mul_f32_e32 v31, v21, v25
	v_mul_f32_e32 v32, v22, v28
	v_fmac_f32_e32 v31, v22, v27
	v_fmac_f32_e32 v32, v21, v26
	v_fmac_f32_e32 v31, v23, v29
	v_fmac_f32_e32 v32, v23, v30
	v_cvt_pk_bf16_f32 v104, v31, v32
	v_lshlrev_b32_e32 v25, 16, v105
	v_and_b32_e32 v26, 0xffff0000, v105
	v_lshlrev_b32_e32 v27, 16, v109
	v_and_b32_e32 v28, 0xffff0000, v109
	v_lshlrev_b32_e32 v29, 16, v113
	v_and_b32_e32 v30, 0xffff0000, v113
	v_mul_f32_e32 v31, v21, v25
	v_mul_f32_e32 v32, v22, v28
	v_fmac_f32_e32 v31, v22, v27
	v_fmac_f32_e32 v32, v21, v26
	v_fmac_f32_e32 v31, v23, v29
	v_fmac_f32_e32 v32, v23, v30
	v_cvt_pk_bf16_f32 v105, v31, v32
	v_lshlrev_b32_e32 v25, 16, v106
	v_and_b32_e32 v26, 0xffff0000, v106
	v_lshlrev_b32_e32 v27, 16, v110
	v_and_b32_e32 v28, 0xffff0000, v110
	v_lshlrev_b32_e32 v29, 16, v114
	v_and_b32_e32 v30, 0xffff0000, v114
	v_mul_f32_e32 v31, v21, v25
	v_mul_f32_e32 v32, v22, v28
	v_fmac_f32_e32 v31, v22, v27
	v_fmac_f32_e32 v32, v21, v26
	v_fmac_f32_e32 v31, v23, v29
	v_fmac_f32_e32 v32, v23, v30
	v_cvt_pk_bf16_f32 v106, v31, v32
	v_lshlrev_b32_e32 v25, 16, v107
	v_and_b32_e32 v26, 0xffff0000, v107
	v_lshlrev_b32_e32 v27, 16, v111
	v_and_b32_e32 v28, 0xffff0000, v111
	v_lshlrev_b32_e32 v29, 16, v115
	v_and_b32_e32 v30, 0xffff0000, v115
	v_mul_f32_e32 v31, v21, v25
	v_mul_f32_e32 v32, v22, v28
	v_fmac_f32_e32 v31, v22, v27
	v_fmac_f32_e32 v32, v21, v26
	v_fmac_f32_e32 v31, v23, v29
	v_fmac_f32_e32 v32, v23, v30
	v_cvt_pk_bf16_f32 v107, v31, v32
	global_store_dwordx4 v14, v[104:107], s[8:9]
	s_add_u32 s8, s8, 0x200000
	s_addc_u32 s9, s9, 0
	v_max3_f32 v20, v176, v177, v178
	v_sub_f32_e32 v21, v176, v20
	v_sub_f32_e32 v22, v177, v20
	v_sub_f32_e32 v23, v178, v20
	v_mul_f32_e32 v21, 0x3fb8aa3b, v21
	v_mul_f32_e32 v22, 0x3fb8aa3b, v22
	v_mul_f32_e32 v23, 0x3fb8aa3b, v23
	v_exp_f32_e32 v21, v21
	v_exp_f32_e32 v22, v22
	v_exp_f32_e32 v23, v23
	s_nop 0
	v_add_f32_e32 v24, v21, v22
	v_add_f32_e32 v24, v23, v24
	v_rcp_f32_e32 v24, v24
	s_nop 0
	v_mul_f32_e32 v21, v21, v24
	v_mul_f32_e32 v22, v22, v24
	v_mul_f32_e32 v23, v23, v24
	s_waitcnt vmcnt(13)
	v_lshlrev_b32_e32 v25, 16, v116
	v_and_b32_e32 v26, 0xffff0000, v116
	v_lshlrev_b32_e32 v27, 16, v120
	v_and_b32_e32 v28, 0xffff0000, v120
	v_lshlrev_b32_e32 v29, 16, v124
	v_and_b32_e32 v30, 0xffff0000, v124
	v_mul_f32_e32 v31, v21, v25
	v_mul_f32_e32 v32, v22, v28
	v_fmac_f32_e32 v31, v22, v27
	v_fmac_f32_e32 v32, v21, v26
	v_fmac_f32_e32 v31, v23, v29
	v_fmac_f32_e32 v32, v23, v30
	v_cvt_pk_bf16_f32 v116, v31, v32
	v_lshlrev_b32_e32 v25, 16, v117
	v_and_b32_e32 v26, 0xffff0000, v117
	v_lshlrev_b32_e32 v27, 16, v121
	v_and_b32_e32 v28, 0xffff0000, v121
	v_lshlrev_b32_e32 v29, 16, v125
	v_and_b32_e32 v30, 0xffff0000, v125
	v_mul_f32_e32 v31, v21, v25
	v_mul_f32_e32 v32, v22, v28
	v_fmac_f32_e32 v31, v22, v27
	v_fmac_f32_e32 v32, v21, v26
	v_fmac_f32_e32 v31, v23, v29
	v_fmac_f32_e32 v32, v23, v30
	v_cvt_pk_bf16_f32 v117, v31, v32
	v_lshlrev_b32_e32 v25, 16, v118
	v_and_b32_e32 v26, 0xffff0000, v118
	v_lshlrev_b32_e32 v27, 16, v122
	v_and_b32_e32 v28, 0xffff0000, v122
	v_lshlrev_b32_e32 v29, 16, v126
	v_and_b32_e32 v30, 0xffff0000, v126
	v_mul_f32_e32 v31, v21, v25
	v_mul_f32_e32 v32, v22, v28
	v_fmac_f32_e32 v31, v22, v27
	v_fmac_f32_e32 v32, v21, v26
	v_fmac_f32_e32 v31, v23, v29
	v_fmac_f32_e32 v32, v23, v30
	v_cvt_pk_bf16_f32 v118, v31, v32
	v_lshlrev_b32_e32 v25, 16, v119
	v_and_b32_e32 v26, 0xffff0000, v119
	v_lshlrev_b32_e32 v27, 16, v123
	v_and_b32_e32 v28, 0xffff0000, v123
	v_lshlrev_b32_e32 v29, 16, v127
	v_and_b32_e32 v30, 0xffff0000, v127
	v_mul_f32_e32 v31, v21, v25
	v_mul_f32_e32 v32, v22, v28
	v_fmac_f32_e32 v31, v22, v27
	v_fmac_f32_e32 v32, v21, v26
	v_fmac_f32_e32 v31, v23, v29
	v_fmac_f32_e32 v32, v23, v30
	v_cvt_pk_bf16_f32 v119, v31, v32
	global_store_dwordx4 v14, v[116:119], s[8:9]
	s_add_u32 s8, s8, 0x200000
	s_addc_u32 s9, s9, 0
	v_max3_f32 v20, v179, v180, v181
	v_sub_f32_e32 v21, v179, v20
	v_sub_f32_e32 v22, v180, v20
	v_sub_f32_e32 v23, v181, v20
	v_mul_f32_e32 v21, 0x3fb8aa3b, v21
	v_mul_f32_e32 v22, 0x3fb8aa3b, v22
	v_mul_f32_e32 v23, 0x3fb8aa3b, v23
	v_exp_f32_e32 v21, v21
	v_exp_f32_e32 v22, v22
	v_exp_f32_e32 v23, v23
	s_nop 0
	v_add_f32_e32 v24, v21, v22
	v_add_f32_e32 v24, v23, v24
	v_rcp_f32_e32 v24, v24
	s_nop 0
	v_mul_f32_e32 v21, v21, v24
	v_mul_f32_e32 v22, v22, v24
	v_mul_f32_e32 v23, v23, v24
	s_waitcnt vmcnt(11)
; __device__ __forceinline__ unsigned cvt_pk_bf16(float lo, float hi) { f32x2_t v = {lo, hi}; bf2_t r = __builtin_convertvector(v, bf2_t); return __builtin_bit_cast(unsigned, r); }
; __device__ __forceinline__ float bflo(unsigned u) { return __uint_as_float(u << 16); }
; __device__ __forceinline__ float bfhi(unsigned u) { return __uint_as_float(u & 0xffff0000u); }
; __device__ __forceinline__ void attn_combine(const Ctx& C) {
;     ...
;         const int tok = idx >> 5, j = (idx >> 3) & 3, c8 = idx & 7;
;         const float l0 = lse[((size_t)0 * M_TOK + tok) * 4 + j], l1 = lse[((size_t)1 * M_TOK + tok) * 4 + j], l2 = lse[((size_t)2 * M_TOK + tok) * 4 + j];
;         const float mx = fmaxf(l0, fmaxf(l1, l2)); float w0 = __expf(l0 - mx), w1 = __expf(l1 - mx), w2 = __expf(l2 - mx); const float inv = 1.0f / (w0 + w1 + w2); w0 *= inv; w1 *= inv; w2 *= inv;
;         const bf16_t* row = pd + (size_t)tok * 2304 + j * 64 + c8 * 8;
;         const u32x4 o0 = *(const u32x4*)row, o1 = *(const u32x4*)(row + 256), o2 = *(const u32x4*)(row + 512);
;         u32x4 o;
;         o.x = cvt_pk_bf16(w0 * bflo(o0.x) + w1 * bflo(o1.x) + w2 * bflo(o2.x), w0 * bfhi(o0.x) + w1 * bfhi(o1.x) + w2 * bfhi(o2.x));
;         o.y = cvt_pk_bf16(w0 * bflo(o0.y) + w1 * bflo(o1.y) + w2 * bflo(o2.y), w0 * bfhi(o0.y) + w1 * bfhi(o1.y) + w2 * bfhi(o2.y));
;         o.z = cvt_pk_bf16(w0 * bflo(o0.z) + w1 * bflo(o1.z) + w2 * bflo(o2.z), w0 * bfhi(o0.z) + w1 * bfhi(o1.z) + w2 * bfhi(o2.z));
;         o.w = cvt_pk_bf16(w0 * bflo(o0.w) + w1 * bflo(o1.w) + w2 * bflo(o2.w), w0 * bfhi(o0.w) + w1 * bfhi(o1.w) + w2 * bfhi(o2.w));
;         *(u32x4*)(yd + (size_t)tok * 256 + j * 64 + c8 * 8) = o;
;     }
	v_lshlrev_b32_e32 v25, 16, v128
	v_and_b32_e32 v26, 0xffff0000, v128
	v_lshlrev_b32_e32 v27, 16, v132
	v_and_b32_e32 v28, 0xffff0000, v132
	v_lshlrev_b32_e32 v29, 16, v136
	v_and_b32_e32 v30, 0xffff0000, v136
	v_mul_f32_e32 v31, v21, v25
	v_mul_f32_e32 v32, v22, v28
	v_fmac_f32_e32 v31, v22, v27
	v_fmac_f32_e32 v32, v21, v26
	v_fmac_f32_e32 v31, v23, v29
	v_fmac_f32_e32 v32, v23, v30
	v_cvt_pk_bf16_f32 v128, v31, v32
	v_lshlrev_b32_e32 v25, 16, v129
	v_and_b32_e32 v26, 0xffff0000, v129
	v_lshlrev_b32_e32 v27, 16, v133
	v_and_b32_e32 v28, 0xffff0000, v133
	v_lshlrev_b32_e32 v29, 16, v137
	v_and_b32_e32 v30, 0xffff0000, v137
	v_mul_f32_e32 v31, v21, v25
	v_mul_f32_e32 v32, v22, v28
	v_fmac_f32_e32 v31, v22, v27
	v_fmac_f32_e32 v32, v21, v26
	v_fmac_f32_e32 v31, v23, v29
	v_fmac_f32_e32 v32, v23, v30
	v_cvt_pk_bf16_f32 v129, v31, v32
	v_lshlrev_b32_e32 v25, 16, v130
	v_and_b32_e32 v26, 0xffff0000, v130
	v_lshlrev_b32_e32 v27, 16, v134
	v_and_b32_e32 v28, 0xffff0000, v134
	v_lshlrev_b32_e32 v29, 16, v138
	v_and_b32_e32 v30, 0xffff0000, v138
	v_mul_f32_e32 v31, v21, v25
	v_mul_f32_e32 v32, v22, v28
	v_fmac_f32_e32 v31, v22, v27
	v_fmac_f32_e32 v32, v21, v26
	v_fmac_f32_e32 v31, v23, v29
	v_fmac_f32_e32 v32, v23, v30
	v_cvt_pk_bf16_f32 v130, v31, v32
	v_lshlrev_b32_e32 v25, 16, v131
	v_and_b32_e32 v26, 0xffff0000, v131
	v_lshlrev_b32_e32 v27, 16, v135
	v_and_b32_e32 v28, 0xffff0000, v135
	v_lshlrev_b32_e32 v29, 16, v139
	v_and_b32_e32 v30, 0xffff0000, v139
	v_mul_f32_e32 v31, v21, v25
	v_mul_f32_e32 v32, v22, v28
	v_fmac_f32_e32 v31, v22, v27
	v_fmac_f32_e32 v32, v21, v26
	v_fmac_f32_e32 v31, v23, v29
	v_fmac_f32_e32 v32, v23, v30
	v_cvt_pk_bf16_f32 v131, v31, v32
	global_store_dwordx4 v14, v[128:131], s[8:9]
	s_add_u32 s8, s8, 0x200000
	s_addc_u32 s9, s9, 0
	v_max3_f32 v20, v188, v189, v190
	v_sub_f32_e32 v21, v188, v20
	v_sub_f32_e32 v22, v189, v20
	v_sub_f32_e32 v23, v190, v20
	v_mul_f32_e32 v21, 0x3fb8aa3b, v21
	v_mul_f32_e32 v22, 0x3fb8aa3b, v22
	v_mul_f32_e32 v23, 0x3fb8aa3b, v23
	v_exp_f32_e32 v21, v21
	v_exp_f32_e32 v22, v22
	v_exp_f32_e32 v23, v23
	s_nop 0
	v_add_f32_e32 v24, v21, v22
	v_add_f32_e32 v24, v23, v24
	v_rcp_f32_e32 v24, v24
	s_nop 0
	v_mul_f32_e32 v21, v21, v24
	v_mul_f32_e32 v22, v22, v24
	v_mul_f32_e32 v23, v23, v24
	s_waitcnt vmcnt(9)
	v_lshlrev_b32_e32 v25, 16, v140
	v_and_b32_e32 v26, 0xffff0000, v140
	v_lshlrev_b32_e32 v27, 16, v144
	v_and_b32_e32 v28, 0xffff0000, v144
	v_lshlrev_b32_e32 v29, 16, v148
	v_and_b32_e32 v30, 0xffff0000, v148
	v_mul_f32_e32 v31, v21, v25
	v_mul_f32_e32 v32, v22, v28
	v_fmac_f32_e32 v31, v22, v27
	v_fmac_f32_e32 v32, v21, v26
	v_fmac_f32_e32 v31, v23, v29
	v_fmac_f32_e32 v32, v23, v30
	v_cvt_pk_bf16_f32 v140, v31, v32
	v_lshlrev_b32_e32 v25, 16, v141
	v_and_b32_e32 v26, 0xffff0000, v141
	v_lshlrev_b32_e32 v27, 16, v145
	v_and_b32_e32 v28, 0xffff0000, v145
	v_lshlrev_b32_e32 v29, 16, v149
	v_and_b32_e32 v30, 0xffff0000, v149
	v_mul_f32_e32 v31, v21, v25
	v_mul_f32_e32 v32, v22, v28
	v_fmac_f32_e32 v31, v22, v27
	v_fmac_f32_e32 v32, v21, v26
	v_fmac_f32_e32 v31, v23, v29
	v_fmac_f32_e32 v32, v23, v30
	v_cvt_pk_bf16_f32 v141, v31, v32
	v_lshlrev_b32_e32 v25, 16, v142
	v_and_b32_e32 v26, 0xffff0000, v142
	v_lshlrev_b32_e32 v27, 16, v146
	v_and_b32_e32 v28, 0xffff0000, v146
	v_lshlrev_b32_e32 v29, 16, v150
	v_and_b32_e32 v30, 0xffff0000, v150
	v_mul_f32_e32 v31, v21, v25
	v_mul_f32_e32 v32, v22, v28
	v_fmac_f32_e32 v31, v22, v27
	v_fmac_f32_e32 v32, v21, v26
	v_fmac_f32_e32 v31, v23, v29
	v_fmac_f32_e32 v32, v23, v30
	v_cvt_pk_bf16_f32 v142, v31, v32
	v_lshlrev_b32_e32 v25, 16, v143
	v_and_b32_e32 v26, 0xffff0000, v143
	v_lshlrev_b32_e32 v27, 16, v147
	v_and_b32_e32 v28, 0xffff0000, v147
	v_lshlrev_b32_e32 v29, 16, v151
	v_and_b32_e32 v30, 0xffff0000, v151
	v_mul_f32_e32 v31, v21, v25
	v_mul_f32_e32 v32, v22, v28
	v_fmac_f32_e32 v31, v22, v27
	v_fmac_f32_e32 v32, v21, v26
	v_fmac_f32_e32 v31, v23, v29
	v_fmac_f32_e32 v32, v23, v30
	v_cvt_pk_bf16_f32 v143, v31, v32
	global_store_dwordx4 v14, v[140:143], s[8:9]
	s_add_u32 s8, s8, 0x200000
	s_addc_u32 s9, s9, 0
	v_max3_f32 v20, v191, v192, v193
	v_sub_f32_e32 v21, v191, v20
	v_sub_f32_e32 v22, v192, v20
	v_sub_f32_e32 v23, v193, v20
	v_mul_f32_e32 v21, 0x3fb8aa3b, v21
	v_mul_f32_e32 v22, 0x3fb8aa3b, v22
	v_mul_f32_e32 v23, 0x3fb8aa3b, v23
	v_exp_f32_e32 v21, v21
	v_exp_f32_e32 v22, v22
	v_exp_f32_e32 v23, v23
	s_nop 0
	v_add_f32_e32 v24, v21, v22
	v_add_f32_e32 v24, v23, v24
	v_rcp_f32_e32 v24, v24
	s_nop 0
	v_mul_f32_e32 v21, v21, v24
	v_mul_f32_e32 v22, v22, v24
	v_mul_f32_e32 v23, v23, v24
	s_waitcnt vmcnt(7)
	v_lshlrev_b32_e32 v25, 16, v152
	v_and_b32_e32 v26, 0xffff0000, v152
	v_lshlrev_b32_e32 v27, 16, v156
	v_and_b32_e32 v28, 0xffff0000, v156
	v_lshlrev_b32_e32 v29, 16, v160
	v_and_b32_e32 v30, 0xffff0000, v160
	v_mul_f32_e32 v31, v21, v25
	v_mul_f32_e32 v32, v22, v28
	v_fmac_f32_e32 v31, v22, v27
	v_fmac_f32_e32 v32, v21, v26
	v_fmac_f32_e32 v31, v23, v29
	v_fmac_f32_e32 v32, v23, v30
	v_cvt_pk_bf16_f32 v152, v31, v32
	v_lshlrev_b32_e32 v25, 16, v153
	v_and_b32_e32 v26, 0xffff0000, v153
	v_lshlrev_b32_e32 v27, 16, v157
	v_and_b32_e32 v28, 0xffff0000, v157
	v_lshlrev_b32_e32 v29, 16, v161
	v_and_b32_e32 v30, 0xffff0000, v161
	v_mul_f32_e32 v31, v21, v25
	v_mul_f32_e32 v32, v22, v28
	v_fmac_f32_e32 v31, v22, v27
	v_fmac_f32_e32 v32, v21, v26
	v_fmac_f32_e32 v31, v23, v29
	v_fmac_f32_e32 v32, v23, v30
	v_cvt_pk_bf16_f32 v153, v31, v32
	v_lshlrev_b32_e32 v25, 16, v154
	v_and_b32_e32 v26, 0xffff0000, v154
	v_lshlrev_b32_e32 v27, 16, v158
	v_and_b32_e32 v28, 0xffff0000, v158
	v_lshlrev_b32_e32 v29, 16, v162
	v_and_b32_e32 v30, 0xffff0000, v162
	v_mul_f32_e32 v31, v21, v25
	v_mul_f32_e32 v32, v22, v28
	v_fmac_f32_e32 v31, v22, v27
	v_fmac_f32_e32 v32, v21, v26
	v_fmac_f32_e32 v31, v23, v29
	v_fmac_f32_e32 v32, v23, v30
	v_cvt_pk_bf16_f32 v154, v31, v32
	v_lshlrev_b32_e32 v25, 16, v155
	v_and_b32_e32 v26, 0xffff0000, v155
	v_lshlrev_b32_e32 v27, 16, v159
	v_and_b32_e32 v28, 0xffff0000, v159
	v_lshlrev_b32_e32 v29, 16, v163
	v_and_b32_e32 v30, 0xffff0000, v163
	v_mul_f32_e32 v31, v21, v25
	v_mul_f32_e32 v32, v22, v28
	v_fmac_f32_e32 v31, v22, v27
	v_fmac_f32_e32 v32, v21, v26
	v_fmac_f32_e32 v31, v23, v29
	v_fmac_f32_e32 v32, v23, v30
	v_cvt_pk_bf16_f32 v155, v31, v32
	global_store_dwordx4 v14, v[152:155], s[8:9]
	s_add_i32 s101, s101, 1
	s_sub_i32 s100, s100, 0x10000
	s_cmp_lg_u32 s101, 1
	s_cbranch_scc1 .Lmy_cmb_pass
